# v14: fold canonicalising v_max into relu max in sq-relu GEMM epilogues (+store-data wait states); counted vmcnt at NA/mixer-B unit tops so previous unit's output stores are not waited for
# speedup vs baseline: 1.0222x; 1.0041x over previous
.Lord_mb:
	s_cmpk_gt_i32 s21, 0x5ff
	s_cbranch_scc1 .Lmb_done
	s_and_b32 s25, s21, 63
	s_lshr_b32 s26, s21, 6
	s_and_b32 s11, s26, 3
	s_lshr_b32 s27, s26, 2
	s_cmp_ge_u32 s27, 3
	s_cselect_b32 s12, 1, 0
	s_mul_i32 s10, s12, 3
	s_sub_i32 s10, s27, s10
	s_lshl_b32 s6, s10, 1
	s_sub_i32 s13, 6, s6
	s_lshr_b32 s7, s25, s13
	s_lshl_b32 s8, 1, s13
	s_add_i32 s8, s8, -1
	s_and_b32 s8, s25, s8
	s_lshl_b32 s8, s8, 8
	s_lshr_b32 s9, 0x4000, s6
	s_add_i32 s15, s9, -1
	s_mul_i32 s28, s12, 0x6000000
	s_add_u32 s4, s94, 0x7800000
	s_addc_u32 s5, s95, 0
	s_add_u32 s4, s4, s28
	s_addc_u32 s5, s5, 0
	s_lshl_b32 s22, s10, 9
	s_lshl_b32 s23, s11, 7
	s_add_i32 s22, s22, s23
	s_add_i32 s22, s22, 0x600
	s_add_i32 s23, s22, 0x600
	s_add_i32 s24, s22, 0xc00
	s_add_u32 s34, s4, s23
	s_addc_u32 s35, s5, 0
	s_add_u32 s36, s4, s24
	s_addc_u32 s37, s5, 0
	s_add_i32 s26, s8, -64
	s_lshl_b32 s25, s31, 5
	s_add_i32 s25, s25, s8
	v_add_u32_e32 v189, s25, v180
	v_lshlrev_b32_e32 v189, s6, v189
	v_add_u32_e32 v189, s7, v189
	v_mul_u32_u24_e32 v190, 0x1800, v189
	v_lshl_add_u32 v190, v181, 4, v190
	v_add_u32_e32 v190, s22, v190
	global_load_dwordx4 v[100:103], v190, s[4:5]
	global_load_dwordx4 v[104:107], v190, s[4:5] offset:32
	global_load_dwordx4 v[108:111], v190, s[4:5] offset:64
	global_load_dwordx4 v[112:115], v190, s[4:5] offset:96
	v_add_u32_e32 v200, s26, v187
	v_med3_i32 v200, v200, 0, s15
	v_lshlrev_b32_e32 v200, s6, v200
	v_add_u32_e32 v200, s7, v200
	v_mul_u32_u24_e32 v200, 0x1800, v200
	v_add_u32_e32 v200, v200, v188
	global_load_dwordx4 v[82:85], v200, s[34:35]
	global_load_dwordx4 v[86:89], v200, s[36:37]
	v_add_u32_e32 v201, s26, v187
	v_add_u32_e32 v201, 64, v201
	v_med3_i32 v201, v201, 0, s15
	v_lshlrev_b32_e32 v201, s6, v201
	v_add_u32_e32 v201, s7, v201
	v_mul_u32_u24_e32 v201, 0x1800, v201
	v_add_u32_e32 v201, v201, v188
	global_load_dwordx4 v[90:93], v201, s[34:35]
	global_load_dwordx4 v[94:97], v201, s[36:37]
	v_add_u32_e32 v202, s26, v187
	v_add_u32_e32 v202, 128, v202
	v_med3_i32 v202, v202, 0, s15
	v_lshlrev_b32_e32 v202, s6, v202
	v_add_u32_e32 v202, s7, v202
	v_mul_u32_u24_e32 v202, 0x1800, v202
	v_add_u32_e32 v202, v202, v188
	global_load_dwordx4 v[214:217], v202, s[34:35]
	global_load_dwordx4 v[218:221], v202, s[36:37]
	v_add_u32_e32 v203, s26, v187
	v_add_u32_e32 v203, 192, v203
	v_med3_i32 v203, v203, 0, s15
	v_lshlrev_b32_e32 v203, s6, v203
	v_add_u32_e32 v203, s7, v203
	v_mul_u32_u24_e32 v203, 0x1800, v203
	v_add_u32_e32 v203, v203, v188
	global_load_dwordx4 v[222:225], v203, s[34:35]
	global_load_dwordx4 v[226:229], v203, s[36:37]
	v_add_u32_e32 v204, s26, v187
	v_add_u32_e32 v204, 256, v204
	v_med3_i32 v204, v204, 0, s15
	v_lshlrev_b32_e32 v204, s6, v204
	v_add_u32_e32 v204, s7, v204
	v_mul_u32_u24_e32 v204, 0x1800, v204
	v_add_u32_e32 v204, v204, v188
	global_load_dwordx4 v[234:237], v204, s[34:35]
	global_load_dwordx4 v[238:241], v204, s[36:37]
	v_add_u32_e32 v205, s26, v187
	v_add_u32_e32 v205, 320, v205
	v_med3_i32 v205, v205, 0, s15
	v_lshlrev_b32_e32 v205, s6, v205
	v_add_u32_e32 v205, s7, v205
	v_mul_u32_u24_e32 v205, 0x1800, v205
	v_add_u32_e32 v205, v205, v188
	global_load_dwordx4 v[242:245], v205, s[34:35]
	global_load_dwordx4 v[246:249], v205, s[36:37]
	s_waitcnt vmcnt(0)
.Lmb_unit:
	s_and_b32 s54, s21, 63
	s_lshr_b32 s55, s21, 6
	s_and_b32 s56, s55, 3
	s_lshr_b32 s57, s55, 2
	s_cmp_ge_u32 s57, 3
	s_cselect_b32 s58, 1, 0
	s_mul_i32 s59, s58, 3
	s_sub_i32 s59, s57, s59
	s_lshl_b32 s60, s59, 1
	s_sub_i32 s61, 6, s60
	s_lshr_b32 s62, s54, s61
	s_lshl_b32 s63, 1, s61
	s_add_i32 s63, s63, -1
	s_and_b32 s63, s54, s63
	s_lshl_b32 s63, s63, 8
	s_lshr_b32 s64, 0x4000, s60
	s_lshl_b32 s28, s59, 24
	s_lshl_b32 s38, s58, 23
	s_add_i32 s28, s28, s38
	s_lshl_b32 s38, s56, 7
	s_add_i32 s28, s28, s38
	s_add_u32 s16, s94, 0x3800000
	s_addc_u32 s17, s95, 0
	s_add_u32 s16, s16, s28
	s_addc_u32 s17, s17, 0
	s_lshl_b32 s28, s59, 19
	s_lshl_b32 s38, s58, 18
	s_add_i32 s28, s28, s38
	s_lshl_b32 s38, s56, 2
	s_add_i32 s28, s28, s38
	s_add_u32 s18, s94, 0x6800000
	s_addc_u32 s19, s95, 0
	s_add_u32 s18, s18, s28
	s_addc_u32 s19, s19, 0
	s_lshl_b32 s65, s31, 5
	s_add_i32 s65, s65, s63
	v_add_u32_e32 v199, s65, v180
	v_lshlrev_b32_e32 v199, s60, v199
	v_add_u32_e32 v199, s62, v199
	s_add_i32 s66, s63, -64
	s_lshl_b32 s67, s29, 6
	s_add_i32 s67, s67, s66
	s_add_i32 s28, s67, 0
	s_cmp_ge_i32 s28, 0
	s_cselect_b32 s50, 1, 0
	s_cmp_lt_i32 s28, s64
	s_cselect_b32 s50, s50, 0
	s_add_i32 s28, s67, 64
	s_cmp_ge_i32 s28, 0
	s_cselect_b32 s51, 1, 0
	s_cmp_lt_i32 s28, s64
	s_cselect_b32 s51, s51, 0
	s_add_i32 s28, s67, 128
	s_cmp_ge_i32 s28, 0
	s_cselect_b32 s52, 1, 0
	s_cmp_lt_i32 s28, s64
	s_cselect_b32 s52, s52, 0
	s_waitcnt vmcnt(5)
	s_barrier
	ds_write_b128 v185, v[82:85]
	ds_write_b128 v185, v[86:89] offset:9216
	ds_write_b128 v185, v[90:93] offset:18432
	ds_write_b128 v185, v[94:97] offset:27648
	ds_write_b128 v185, v[214:217] offset:36864
	ds_write_b128 v185, v[218:221] offset:46080
	ds_write_b128 v206, v[222:225]
	ds_write_b128 v206, v[226:229] offset:9216
	ds_write_b128 v206, v[234:237] offset:18432
	ds_write_b128 v206, v[238:241] offset:27648
	ds_write_b128 v206, v[242:245] offset:36864
	ds_write_b128 v206, v[246:249] offset:46080
	s_waitcnt lgkmcnt(0)
	s_barrier
	s_bitcmp1_b32 s31, 0
	s_cbranch_scc1 .Lmb_odd
	ds_read_b128 v[148:151], v183
	ds_read_b128 v[152:155], v183 offset:32
	ds_read_b128 v[156:159], v183 offset:64
	ds_read_b128 v[160:163], v183 offset:96
	ds_read_b128 v[164:167], v183 offset:4608
	ds_read_b128 v[168:171], v183 offset:4640
	ds_read_b128 v[172:175], v183 offset:4672
	ds_read_b128 v[176:179], v183 offset:4704
	s_waitcnt lgkmcnt(7)
	v_mfma_f32_32x32x16_bf16 v[2:17], v[148:151], v[100:103], 0
	s_waitcnt lgkmcnt(6)
	v_mfma_f32_32x32x16_bf16 v[2:17], v[152:155], v[104:107], v[2:17]
	s_waitcnt lgkmcnt(5)
	v_mfma_f32_32x32x16_bf16 v[2:17], v[156:159], v[108:111], v[2:17]
	s_waitcnt lgkmcnt(4)
	v_mfma_f32_32x32x16_bf16 v[2:17], v[160:163], v[112:115], v[2:17]
	ds_read_b128 v[148:151], v183 offset:18432
	ds_read_b128 v[152:155], v183 offset:18464
	ds_read_b128 v[156:159], v183 offset:18496
	ds_read_b128 v[160:163], v183 offset:18528
	s_waitcnt lgkmcnt(7)
	v_mfma_f32_32x32x16_bf16 v[18:33], v[164:167], v[100:103], 0
	s_waitcnt lgkmcnt(6)
	v_mfma_f32_32x32x16_bf16 v[18:33], v[168:171], v[104:107], v[18:33]
	s_waitcnt lgkmcnt(5)
	v_mfma_f32_32x32x16_bf16 v[18:33], v[172:175], v[108:111], v[18:33]
	s_waitcnt lgkmcnt(4)
	v_mfma_f32_32x32x16_bf16 v[18:33], v[176:179], v[112:115], v[18:33]
	ds_read_b128 v[164:167], v183 offset:23040
	ds_read_b128 v[168:171], v183 offset:23072
	ds_read_b128 v[172:175], v183 offset:23104
	ds_read_b128 v[176:179], v183 offset:23136
	s_waitcnt lgkmcnt(7)
	v_mfma_f32_32x32x16_bf16 v[34:49], v[148:151], v[100:103], 0
	s_waitcnt lgkmcnt(6)
	v_mfma_f32_32x32x16_bf16 v[34:49], v[152:155], v[104:107], v[34:49]
	s_waitcnt lgkmcnt(5)
	v_mfma_f32_32x32x16_bf16 v[34:49], v[156:159], v[108:111], v[34:49]
	s_waitcnt lgkmcnt(4)
	v_mfma_f32_32x32x16_bf16 v[34:49], v[160:163], v[112:115], v[34:49]
	ds_read_b128 v[148:151], v183 offset:36864
	ds_read_b128 v[152:155], v183 offset:36896
	ds_read_b128 v[156:159], v183 offset:36928
	ds_read_b128 v[160:163], v183 offset:36960
	s_waitcnt lgkmcnt(7)
	v_mfma_f32_32x32x16_bf16 v[50:65], v[164:167], v[100:103], 0
	s_waitcnt lgkmcnt(6)
	v_mfma_f32_32x32x16_bf16 v[50:65], v[168:171], v[104:107], v[50:65]
	s_waitcnt lgkmcnt(5)
	v_mfma_f32_32x32x16_bf16 v[50:65], v[172:175], v[108:111], v[50:65]
	s_waitcnt lgkmcnt(4)
	v_mfma_f32_32x32x16_bf16 v[50:65], v[176:179], v[112:115], v[50:65]
	s_waitcnt lgkmcnt(3)
	v_mfma_f32_32x32x16_bf16 v[66:81], v[148:151], v[100:103], 0
	s_waitcnt lgkmcnt(2)
	v_mfma_f32_32x32x16_bf16 v[66:81], v[152:155], v[104:107], v[66:81]
	s_waitcnt lgkmcnt(1)
	v_mfma_f32_32x32x16_bf16 v[66:81], v[156:159], v[108:111], v[66:81]
	s_waitcnt lgkmcnt(0)
	v_mfma_f32_32x32x16_bf16 v[66:81], v[160:163], v[112:115], v[66:81]
	s_add_i32 s33, s21, s53
	s_cmp_le_u32 s20, 1
	s_cbranch_scc1 .Lmb_nopf0
	s_cmpk_gt_i32 s33, 0x5ff
	s_cbranch_scc1 .Lmb_nopf0
	s_and_b32 s25, s33, 63
	s_lshr_b32 s26, s33, 6
	s_and_b32 s11, s26, 3
	s_lshr_b32 s27, s26, 2
	s_cmp_ge_u32 s27, 3
	s_cselect_b32 s12, 1, 0
	s_mul_i32 s10, s12, 3
	s_sub_i32 s10, s27, s10
	s_lshl_b32 s6, s10, 1
	s_sub_i32 s13, 6, s6
	s_lshr_b32 s7, s25, s13
	s_lshl_b32 s8, 1, s13
	s_add_i32 s8, s8, -1
	s_and_b32 s8, s25, s8
	s_lshl_b32 s8, s8, 8
	s_lshr_b32 s9, 0x4000, s6
	s_add_i32 s15, s9, -1
	s_mul_i32 s28, s12, 0x6000000
	s_add_u32 s4, s94, 0x7800000
	s_addc_u32 s5, s95, 0
	s_add_u32 s4, s4, s28
	s_addc_u32 s5, s5, 0
	s_lshl_b32 s22, s10, 9
	s_lshl_b32 s23, s11, 7
	s_add_i32 s22, s22, s23
	s_add_i32 s22, s22, 0x600
	s_add_i32 s23, s22, 0x600
	s_add_i32 s24, s22, 0xc00
	s_add_u32 s34, s4, s23
	s_addc_u32 s35, s5, 0
	s_add_u32 s36, s4, s24
	s_addc_u32 s37, s5, 0
	s_add_i32 s26, s8, -64
	s_lshl_b32 s25, s31, 5
	s_add_i32 s25, s25, s8
	v_add_u32_e32 v189, s25, v180
	v_lshlrev_b32_e32 v189, s6, v189
	v_add_u32_e32 v189, s7, v189
	v_mul_u32_u24_e32 v190, 0x1800, v189
	v_lshl_add_u32 v190, v181, 4, v190
	v_add_u32_e32 v190, s22, v190
	global_load_dwordx4 v[100:103], v190, s[4:5]
	global_load_dwordx4 v[104:107], v190, s[4:5] offset:32
	global_load_dwordx4 v[108:111], v190, s[4:5] offset:64
	global_load_dwordx4 v[112:115], v190, s[4:5] offset:96
	v_add_u32_e32 v200, s26, v187
	v_med3_i32 v200, v200, 0, s15
	v_lshlrev_b32_e32 v200, s6, v200
	v_add_u32_e32 v200, s7, v200
	v_mul_u32_u24_e32 v200, 0x1800, v200
	v_add_u32_e32 v200, v200, v188
	global_load_dwordx4 v[82:85], v200, s[34:35]
	global_load_dwordx4 v[86:89], v200, s[36:37]
	v_add_u32_e32 v201, s26, v187
	v_add_u32_e32 v201, 64, v201
	v_med3_i32 v201, v201, 0, s15
	v_lshlrev_b32_e32 v201, s6, v201
	v_add_u32_e32 v201, s7, v201
	v_mul_u32_u24_e32 v201, 0x1800, v201
	v_add_u32_e32 v201, v201, v188
	global_load_dwordx4 v[90:93], v201, s[34:35]
	global_load_dwordx4 v[94:97], v201, s[36:37]
	v_add_u32_e32 v202, s26, v187
	v_add_u32_e32 v202, 128, v202
	v_med3_i32 v202, v202, 0, s15
	v_lshlrev_b32_e32 v202, s6, v202
	v_add_u32_e32 v202, s7, v202
	v_mul_u32_u24_e32 v202, 0x1800, v202
	v_add_u32_e32 v202, v202, v188
	global_load_dwordx4 v[214:217], v202, s[34:35]
	global_load_dwordx4 v[218:221], v202, s[36:37]
	v_add_u32_e32 v203, s26, v187
	v_add_u32_e32 v203, 192, v203
	v_med3_i32 v203, v203, 0, s15
	v_lshlrev_b32_e32 v203, s6, v203
	v_add_u32_e32 v203, s7, v203
	v_mul_u32_u24_e32 v203, 0x1800, v203
	v_add_u32_e32 v203, v203, v188
	global_load_dwordx4 v[222:225], v203, s[34:35]
	global_load_dwordx4 v[226:229], v203, s[36:37]
	v_add_u32_e32 v204, s26, v187
	v_add_u32_e32 v204, 256, v204
	v_med3_i32 v204, v204, 0, s15
	v_lshlrev_b32_e32 v204, s6, v204
	v_add_u32_e32 v204, s7, v204
	v_mul_u32_u24_e32 v204, 0x1800, v204
	v_add_u32_e32 v204, v204, v188
	global_load_dwordx4 v[234:237], v204, s[34:35]
	global_load_dwordx4 v[238:241], v204, s[36:37]
	v_add_u32_e32 v205, s26, v187
	v_add_u32_e32 v205, 320, v205
	v_med3_i32 v205, v205, 0, s15
	v_lshlrev_b32_e32 v205, s6, v205
	v_add_u32_e32 v205, s7, v205
	v_mul_u32_u24_e32 v205, 0x1800, v205
	v_add_u32_e32 v205, v205, v188
	global_load_dwordx4 v[242:245], v205, s[34:35]
	global_load_dwordx4 v[246:249], v205, s[36:37]

.LBB0_656:
	v_lshl_add_u32 v154, s28, 8, v1
	v_max_f32_e32 v122, 0, v122
	v_lshl_or_b32 v146, s62, 8, v149
	v_ashrrev_i32_e32 v155, 31, v154
	v_mul_f32_e32 v153, v122, v122
	v_max_f32_e32 v123, 0, v123
	v_max_f32_e32 v124, 0, v124
	v_ashrrev_i32_e32 v147, 31, v146
	v_lshlrev_b64 v[156:157], 13, v[154:155]
	v_max_f32_e32 v122, 0, v127
	v_mul_f32_e32 v127, v123, v123
	v_max_f32_e32 v123, v128, v128
	v_mul_f32_e32 v128, v124, v124
	v_lshl_add_u64 v[156:157], s[6:7], 0, v[156:157]
	v_lshlrev_b64 v[158:159], 1, v[146:147]
	v_max_f32_e32 v126, 0, v126
	v_mul_f32_e32 v122, v122, v122
	v_max_f32_e32 v123, 0, v123
	v_max_f32_e32 v124, 0, v129
	v_max_f32_e32 v125, 0, v125
	v_lshl_add_u64 v[146:147], v[156:157], 0, v[158:159]
	v_mul_f32_e32 v126, v126, v126
	v_mul_f32_e32 v123, v123, v123
	v_mul_f32_e32 v124, v124, v124
	v_mul_f32_e32 v125, v125, v125
	v_cvt_pk_bf16_f32 v122, v126, v122
	v_max_f32_e32 v114, 0, v114
	v_cvt_pk_bf16_f32 v123, v123, v124
	v_cvt_pk_bf16_f32 v124, v153, v127
	v_cvt_pk_bf16_f32 v125, v128, v125
	global_store_dwordx4 v[146:147], v[122:125], off
	v_max_f32_e32 v115, 0, v115
	v_max_f32_e32 v116, 0, v116
	v_mul_f32_e32 v122, v114, v114
	v_max_f32_e32 v114, 0, v119
	v_mul_f32_e32 v119, v115, v115
	v_max_f32_e32 v115, v120, v120
	v_mul_f32_e32 v120, v116, v116
	v_max_f32_e32 v118, 0, v118
	v_mul_f32_e32 v114, v114, v114
	v_max_f32_e32 v115, 0, v115
	v_max_f32_e32 v116, 0, v121
	v_max_f32_e32 v117, 0, v117
	v_mul_f32_e32 v118, v118, v118
	v_mul_f32_e32 v115, v115, v115
	v_mul_f32_e32 v116, v116, v116
	v_mul_f32_e32 v117, v117, v117
	v_cvt_pk_bf16_f32 v114, v118, v114
	v_cvt_pk_bf16_f32 v115, v115, v116
	v_cvt_pk_bf16_f32 v116, v122, v119
	v_cvt_pk_bf16_f32 v117, v120, v117
	global_store_dwordx4 v[146:147], v[114:117], off offset:256
	v_max_f32_e32 v106, 0, v106
	s_nop 0
	v_or_b32_e32 v114, 16, v154
	v_ashrrev_i32_e32 v115, 31, v114
	v_mul_f32_e32 v116, v106, v106
	v_max_f32_e32 v107, 0, v107
	v_max_f32_e32 v108, 0, v108
	v_lshlrev_b64 v[114:115], 13, v[114:115]
	v_max_f32_e32 v106, 0, v111
	v_mul_f32_e32 v111, v107, v107
	v_max_f32_e32 v107, v112, v112
	v_mul_f32_e32 v112, v108, v108
	v_lshl_add_u64 v[114:115], s[6:7], 0, v[114:115]
	v_max_f32_e32 v110, 0, v110
	v_mul_f32_e32 v106, v106, v106
	v_max_f32_e32 v107, 0, v107
	v_max_f32_e32 v108, 0, v113
	v_max_f32_e32 v109, 0, v109
	v_lshl_add_u64 v[114:115], v[114:115], 0, v[158:159]
	v_mul_f32_e32 v110, v110, v110
	v_mul_f32_e32 v107, v107, v107
	v_mul_f32_e32 v108, v108, v108
	v_mul_f32_e32 v109, v109, v109
	v_cvt_pk_bf16_f32 v106, v110, v106
	v_max_f32_e32 v98, 0, v98
	v_cvt_pk_bf16_f32 v107, v107, v108
	v_cvt_pk_bf16_f32 v108, v116, v111
	v_cvt_pk_bf16_f32 v109, v112, v109
	global_store_dwordx4 v[114:115], v[106:109], off
	v_max_f32_e32 v99, 0, v99
	v_max_f32_e32 v100, 0, v100
	v_mul_f32_e32 v106, v98, v98
	v_max_f32_e32 v98, 0, v103
	v_mul_f32_e32 v103, v99, v99
	v_max_f32_e32 v99, v104, v104
	v_mul_f32_e32 v104, v100, v100
	v_max_f32_e32 v102, 0, v102
	v_mul_f32_e32 v98, v98, v98
	v_max_f32_e32 v99, 0, v99
	v_max_f32_e32 v100, 0, v105
	v_max_f32_e32 v101, 0, v101
	v_mul_f32_e32 v102, v102, v102
	v_mul_f32_e32 v99, v99, v99
	v_mul_f32_e32 v100, v100, v100
	v_mul_f32_e32 v101, v101, v101
	v_cvt_pk_bf16_f32 v98, v102, v98
	v_cvt_pk_bf16_f32 v99, v99, v100
	v_cvt_pk_bf16_f32 v100, v106, v103
	v_cvt_pk_bf16_f32 v101, v104, v101
	global_store_dwordx4 v[114:115], v[98:101], off offset:256
	v_max_f32_e32 v90, 0, v90
	s_nop 0
	v_or_b32_e32 v98, 32, v154
	v_ashrrev_i32_e32 v99, 31, v98
	v_mul_f32_e32 v100, v90, v90
	v_max_f32_e32 v91, 0, v91
	v_max_f32_e32 v92, 0, v92
	v_lshlrev_b64 v[98:99], 13, v[98:99]
	v_max_f32_e32 v90, 0, v95
	v_mul_f32_e32 v95, v91, v91
	v_max_f32_e32 v91, v96, v96
	v_mul_f32_e32 v96, v92, v92
	v_lshl_add_u64 v[98:99], s[6:7], 0, v[98:99]
	v_max_f32_e32 v94, 0, v94
	v_mul_f32_e32 v90, v90, v90
	v_max_f32_e32 v91, 0, v91
	v_max_f32_e32 v92, 0, v97
	v_max_f32_e32 v93, 0, v93
	v_lshl_add_u64 v[98:99], v[98:99], 0, v[158:159]
	v_mul_f32_e32 v94, v94, v94
	v_mul_f32_e32 v91, v91, v91
	v_mul_f32_e32 v92, v92, v92
	v_mul_f32_e32 v93, v93, v93
	v_cvt_pk_bf16_f32 v90, v94, v90
	v_max_f32_e32 v82, 0, v82
	v_cvt_pk_bf16_f32 v91, v91, v92
	v_cvt_pk_bf16_f32 v92, v100, v95
	v_cvt_pk_bf16_f32 v93, v96, v93
	global_store_dwordx4 v[98:99], v[90:93], off
	v_max_f32_e32 v83, 0, v83
	v_max_f32_e32 v84, 0, v84
	v_mul_f32_e32 v90, v82, v82
	v_max_f32_e32 v82, 0, v87
	v_mul_f32_e32 v87, v83, v83
	v_max_f32_e32 v83, v88, v88
	v_mul_f32_e32 v88, v84, v84
	v_max_f32_e32 v86, 0, v86
	v_mul_f32_e32 v82, v82, v82
	v_max_f32_e32 v83, 0, v83
	v_max_f32_e32 v84, 0, v89
	v_max_f32_e32 v85, 0, v85
	v_mul_f32_e32 v86, v86, v86
	v_mul_f32_e32 v83, v83, v83
	v_mul_f32_e32 v84, v84, v84
	v_mul_f32_e32 v85, v85, v85
	v_cvt_pk_bf16_f32 v82, v86, v82
	v_cvt_pk_bf16_f32 v83, v83, v84
	v_cvt_pk_bf16_f32 v84, v90, v87
	v_cvt_pk_bf16_f32 v85, v88, v85
	global_store_dwordx4 v[98:99], v[82:85], off offset:256
	v_max_f32_e32 v74, 0, v74
	s_nop 0
	v_or_b32_e32 v82, 48, v154
	v_ashrrev_i32_e32 v83, 31, v82
	v_mul_f32_e32 v84, v74, v74
	v_max_f32_e32 v75, 0, v75
	v_max_f32_e32 v76, 0, v76
	v_lshlrev_b64 v[82:83], 13, v[82:83]
	v_max_f32_e32 v74, 0, v79
	v_mul_f32_e32 v79, v75, v75
	v_max_f32_e32 v75, v80, v80
	v_mul_f32_e32 v80, v76, v76
	v_lshl_add_u64 v[82:83], s[6:7], 0, v[82:83]
	v_max_f32_e32 v78, 0, v78
	v_mul_f32_e32 v74, v74, v74
	v_max_f32_e32 v75, 0, v75
	v_max_f32_e32 v76, 0, v81
	v_max_f32_e32 v77, 0, v77
	v_lshl_add_u64 v[82:83], v[82:83], 0, v[158:159]
	v_mul_f32_e32 v78, v78, v78
	v_mul_f32_e32 v75, v75, v75
	v_mul_f32_e32 v76, v76, v76
	v_mul_f32_e32 v77, v77, v77
	v_cvt_pk_bf16_f32 v74, v78, v74
	v_max_f32_e32 v66, 0, v66
	v_max_f32_e32 v67, 0, v67
	v_max_f32_e32 v68, 0, v68
	v_cvt_pk_bf16_f32 v75, v75, v76
	v_cvt_pk_bf16_f32 v76, v84, v79
	v_cvt_pk_bf16_f32 v77, v80, v77
	global_store_dwordx4 v[82:83], v[74:77], off
	s_nop 1
	v_mul_f32_e32 v74, v66, v66
	v_max_f32_e32 v66, v71, v71
	v_mul_f32_e32 v71, v67, v67
	v_max_f32_e32 v67, v72, v72
	v_mul_f32_e32 v72, v68, v68
	v_max_f32_e32 v66, 0, v66
	v_max_f32_e32 v67, 0, v67
	v_max_f32_e32 v68, 0, v73
	v_max_f32_e32 v70, 0, v70
	v_mul_f32_e32 v66, v66, v66
	v_mul_f32_e32 v67, v67, v67
	v_max_f32_e32 v69, 0, v69
	v_mul_f32_e32 v68, v68, v68
	v_mul_f32_e32 v70, v70, v70
	v_mul_f32_e32 v69, v69, v69
	v_cvt_pk_bf16_f32 v66, v70, v66
	v_cvt_pk_bf16_f32 v67, v67, v68
	v_cvt_pk_bf16_f32 v68, v74, v71
	v_max_f32_e32 v58, 0, v58
	v_cvt_pk_bf16_f32 v69, v72, v69
	global_store_dwordx4 v[82:83], v[66:69], off offset:256
	v_max_f32_e32 v59, 0, v59
	s_nop 0
	v_mul_f32_e32 v68, v58, v58
	v_max_f32_e32 v60, 0, v60
	v_max_f32_e32 v62, 0, v62
	v_max_f32_e32 v58, 0, v63
	v_mul_f32_e32 v63, v59, v59
	v_max_f32_e32 v59, v64, v64
	v_mul_f32_e32 v64, v60, v60
	v_mul_f32_e32 v62, v62, v62
	v_mul_f32_e32 v58, v58, v58
	v_max_f32_e32 v59, 0, v59
	v_max_f32_e32 v60, 0, v65
	v_mul_f32_e32 v59, v59, v59
	v_max_f32_e32 v61, 0, v61
	v_mul_f32_e32 v60, v60, v60
	v_cvt_pk_bf16_f32 v58, v62, v58
	v_add_co_u32_e32 v62, vcc, s58, v146
	v_mul_f32_e32 v61, v61, v61
	v_cvt_pk_bf16_f32 v59, v59, v60
	v_cvt_pk_bf16_f32 v60, v68, v63
	v_addc_co_u32_e32 v63, vcc, 0, v147, vcc
	v_max_f32_e32 v50, 0, v50
	v_max_f32_e32 v51, 0, v51
	v_max_f32_e32 v52, 0, v52
	v_cvt_pk_bf16_f32 v61, v64, v61
	global_store_dwordx4 v[62:63], v[58:61], off
	s_nop 1
	v_mul_f32_e32 v58, v50, v50
	v_max_f32_e32 v50, v55, v55
	v_mul_f32_e32 v55, v51, v51
	v_max_f32_e32 v51, v56, v56
	v_mul_f32_e32 v56, v52, v52
	v_max_f32_e32 v50, 0, v50
	v_max_f32_e32 v51, 0, v51
	v_max_f32_e32 v52, 0, v57
	v_max_f32_e32 v54, 0, v54
	v_mul_f32_e32 v50, v50, v50
	v_mul_f32_e32 v51, v51, v51
	v_max_f32_e32 v53, 0, v53
	v_mul_f32_e32 v52, v52, v52
	v_lshl_add_u64 v[66:67], v[146:147], 0, s[12:13]
	v_mul_f32_e32 v54, v54, v54
	v_mul_f32_e32 v53, v53, v53
	v_cvt_pk_bf16_f32 v50, v54, v50
	v_cvt_pk_bf16_f32 v51, v51, v52
	v_cvt_pk_bf16_f32 v52, v58, v55
	v_max_f32_e32 v42, 0, v42
	v_cvt_pk_bf16_f32 v53, v56, v53
	global_store_dwordx4 v[66:67], v[50:53], off offset:256
	v_max_f32_e32 v43, 0, v43
	s_nop 0
	v_mul_f32_e32 v52, v42, v42
	v_max_f32_e32 v44, 0, v44
	v_max_f32_e32 v46, 0, v46
	v_max_f32_e32 v42, 0, v47
	v_mul_f32_e32 v47, v43, v43
	v_max_f32_e32 v43, v48, v48
	v_mul_f32_e32 v48, v44, v44
	v_mul_f32_e32 v46, v46, v46
	v_mul_f32_e32 v42, v42, v42
	v_max_f32_e32 v43, 0, v43
	v_max_f32_e32 v44, 0, v49
	v_mul_f32_e32 v43, v43, v43
	v_max_f32_e32 v45, 0, v45
	v_mul_f32_e32 v44, v44, v44
	v_cvt_pk_bf16_f32 v42, v46, v42
	v_add_co_u32_e32 v46, vcc, s59, v146
	v_mul_f32_e32 v45, v45, v45
	v_cvt_pk_bf16_f32 v43, v43, v44
	v_cvt_pk_bf16_f32 v44, v52, v47
	v_addc_co_u32_e32 v47, vcc, 0, v147, vcc
	v_max_f32_e32 v34, 0, v34
	v_max_f32_e32 v35, 0, v35
	v_max_f32_e32 v36, 0, v36
	v_cvt_pk_bf16_f32 v45, v48, v45
	global_store_dwordx4 v[46:47], v[42:45], off
	s_nop 1
	v_mul_f32_e32 v42, v34, v34
	v_max_f32_e32 v34, v39, v39
	v_mul_f32_e32 v39, v35, v35
	v_max_f32_e32 v35, v40, v40
	v_mul_f32_e32 v40, v36, v36
	v_max_f32_e32 v34, 0, v34
	v_max_f32_e32 v35, 0, v35
	v_max_f32_e32 v36, 0, v41
	v_max_f32_e32 v38, 0, v38
	v_mul_f32_e32 v34, v34, v34
	v_mul_f32_e32 v35, v35, v35
	v_max_f32_e32 v37, 0, v37
	v_mul_f32_e32 v36, v36, v36
	v_lshl_add_u64 v[50:51], v[146:147], 0, s[14:15]
	v_mul_f32_e32 v38, v38, v38
	v_mul_f32_e32 v37, v37, v37
	v_cvt_pk_bf16_f32 v34, v38, v34
	v_cvt_pk_bf16_f32 v35, v35, v36
	v_cvt_pk_bf16_f32 v36, v42, v39
	v_max_f32_e32 v26, 0, v26
	v_cvt_pk_bf16_f32 v37, v40, v37
	global_store_dwordx4 v[50:51], v[34:37], off offset:256
	v_max_f32_e32 v27, 0, v27
	s_nop 0
	v_mul_f32_e32 v36, v26, v26
	v_max_f32_e32 v28, 0, v28
	v_max_f32_e32 v30, 0, v30
	v_max_f32_e32 v26, 0, v31
	v_mul_f32_e32 v31, v27, v27
	v_max_f32_e32 v27, v32, v32
	v_mul_f32_e32 v32, v28, v28
	v_mul_f32_e32 v30, v30, v30
	v_mul_f32_e32 v26, v26, v26
	v_max_f32_e32 v27, 0, v27
	v_max_f32_e32 v28, 0, v33
	v_mul_f32_e32 v27, v27, v27
	v_max_f32_e32 v29, 0, v29
	v_mul_f32_e32 v28, v28, v28
	v_cvt_pk_bf16_f32 v26, v30, v26
	v_add_co_u32_e32 v30, vcc, s60, v146
	v_mul_f32_e32 v29, v29, v29
	v_cvt_pk_bf16_f32 v27, v27, v28
	v_cvt_pk_bf16_f32 v28, v36, v31
	v_addc_co_u32_e32 v31, vcc, 0, v147, vcc
	v_max_f32_e32 v18, 0, v18
	v_max_f32_e32 v19, 0, v19
	v_max_f32_e32 v20, 0, v20
	v_cvt_pk_bf16_f32 v29, v32, v29
	global_store_dwordx4 v[30:31], v[26:29], off
	s_nop 1
	v_mul_f32_e32 v26, v18, v18
	v_max_f32_e32 v18, v23, v23
	v_mul_f32_e32 v23, v19, v19
	v_max_f32_e32 v19, v24, v24
	v_mul_f32_e32 v24, v20, v20
	v_max_f32_e32 v18, 0, v18
	v_max_f32_e32 v19, 0, v19
	v_max_f32_e32 v20, 0, v25
	v_max_f32_e32 v22, 0, v22
	v_mul_f32_e32 v18, v18, v18
	v_mul_f32_e32 v19, v19, v19
	v_max_f32_e32 v21, 0, v21
	v_mul_f32_e32 v20, v20, v20
	v_lshl_add_u64 v[34:35], v[146:147], 0, s[16:17]
	v_mul_f32_e32 v22, v22, v22
	v_mul_f32_e32 v21, v21, v21
	v_cvt_pk_bf16_f32 v18, v22, v18
	v_cvt_pk_bf16_f32 v19, v19, v20
	v_cvt_pk_bf16_f32 v20, v26, v23
	v_max_f32_e32 v10, 0, v10
	v_cvt_pk_bf16_f32 v21, v24, v21
	global_store_dwordx4 v[34:35], v[18:21], off offset:256
	v_max_f32_e32 v11, 0, v11
	s_nop 0
	v_mul_f32_e32 v20, v10, v10
	v_max_f32_e32 v12, 0, v12
	v_max_f32_e32 v14, 0, v14
	v_max_f32_e32 v10, 0, v15
	v_mul_f32_e32 v15, v11, v11
	v_max_f32_e32 v11, v16, v16
	v_mul_f32_e32 v16, v12, v12
	v_mul_f32_e32 v14, v14, v14
	v_mul_f32_e32 v10, v10, v10
	v_max_f32_e32 v11, 0, v11
	v_max_f32_e32 v12, 0, v17
	v_mul_f32_e32 v11, v11, v11
	v_max_f32_e32 v13, 0, v13
	v_mul_f32_e32 v12, v12, v12
	v_cvt_pk_bf16_f32 v10, v14, v10
	v_add_co_u32_e32 v14, vcc, s61, v146
	v_mul_f32_e32 v13, v13, v13
	v_cvt_pk_bf16_f32 v11, v11, v12
	v_cvt_pk_bf16_f32 v12, v20, v15
	v_addc_co_u32_e32 v15, vcc, 0, v147, vcc
	v_max_f32_e32 v2, 0, v2
	v_max_f32_e32 v3, 0, v3
	v_max_f32_e32 v4, 0, v4
	v_cvt_pk_bf16_f32 v13, v16, v13
	global_store_dwordx4 v[14:15], v[10:13], off
	s_nop 1
	v_mul_f32_e32 v10, v2, v2
	v_max_f32_e32 v2, v7, v7
	v_mul_f32_e32 v7, v3, v3
	v_max_f32_e32 v3, v8, v8
	v_mul_f32_e32 v8, v4, v4
	v_max_f32_e32 v2, 0, v2
	v_max_f32_e32 v3, 0, v3
	v_max_f32_e32 v4, 0, v9
	v_max_f32_e32 v5, 0, v5
	v_lshl_add_u64 v[18:19], v[146:147], 0, s[18:19]
	v_max_f32_e32 v6, 0, v6
	v_mul_f32_e32 v2, v2, v2
	v_mul_f32_e32 v3, v3, v3
	v_mul_f32_e32 v4, v4, v4
	v_mul_f32_e32 v5, v5, v5
	s_andn2_b64 vcc, exec, s[0:1]
	s_mov_b64 s[0:1], -1
	v_mul_f32_e32 v6, v6, v6
	v_cvt_pk_bf16_f32 v2, v6, v2
	v_cvt_pk_bf16_f32 v3, v3, v4
	v_cvt_pk_bf16_f32 v4, v10, v7
	v_cvt_pk_bf16_f32 v5, v8, v5
	global_store_dwordx4 v[18:19], v[2:5], off offset:256
	s_cbranch_vccnz .LBB0_645
	s_andn2_b64 vcc, exec, s[4:5]
	s_cbranch_vccnz .LBB0_644
	s_barrier
	s_branch .LBB0_644

.Lord_na:
	s_cmpk_gt_i32 s21, 0x7ff
	s_cbranch_scc1 .Lna_done
	s_lshr_b32 s6, s21, 6
	s_and_b32 s7, s21, 63
	s_lshr_b32 s8, s6, 4
	s_and_b32 s9, s6, 15
	s_lshl_b32 s10, s7, 2
	s_add_i32 s22, s10, -4
	s_max_i32 s22, s22, 0
	s_min_i32 s22, s22, 0xf8
	s_mul_i32 s11, s8, 0x6000000
	s_lshl_b32 s12, s9, 7
	s_add_u32 s4, s94, 0x7800000
	s_addc_u32 s5, s95, 0
	s_add_u32 s4, s4, s11
	s_addc_u32 s5, s5, 0
	s_add_u32 s4, s4, s12
	s_addc_u32 s5, s5, 0
	s_add_u32 s34, s4, 0x800
	s_addc_u32 s35, s5, 0
	s_add_u32 s36, s4, 0x1000
	s_addc_u32 s37, s5, 0
	s_mul_i32 s11, s9, 0x744
	s_add_u32 s38, s86, s11
	s_addc_u32 s39, s87, 0
	s_lshl_b32 s26, s30, 1
	s_add_i32 s26, s26, s10
	v_lshrrev_b32_e32 v217, 4, v196
	v_add_u32_e32 v217, s26, v217
	v_lshl_add_u32 v217, v217, 6, v198
	v_mul_u32_u24_e32 v217, 0x1800, v217
	v_lshl_add_u32 v217, v197, 4, v217
	global_load_dwordx4 v[82:85], v217, s[4:5]
	global_load_dwordx4 v[86:89], v217, s[4:5] offset:32
	global_load_dwordx4 v[90:93], v217, s[4:5] offset:64
	global_load_dwordx4 v[94:97], v217, s[4:5] offset:96
	s_add_i32 s27, s22, 0
	s_min_i32 s27, s27, 0xff
	s_mul_i32 s27, s27, 0x60000
	v_add_u32_e32 v223, s27, v231
	global_load_dwordx4 v[146:149], v223, s[34:35]
	global_load_dwordx4 v[150:153], v223, s[36:37]
	s_add_i32 s27, s22, 1
	s_min_i32 s27, s27, 0xff
	s_mul_i32 s27, s27, 0x60000
	v_add_u32_e32 v224, s27, v231
	global_load_dwordx4 v[154:157], v224, s[34:35]
	global_load_dwordx4 v[158:161], v224, s[36:37]
	s_add_i32 s27, s22, 2
	s_min_i32 s27, s27, 0xff
	s_mul_i32 s27, s27, 0x60000
	v_add_u32_e32 v225, s27, v231
	global_load_dwordx4 v[162:165], v225, s[34:35]
	global_load_dwordx4 v[166:169], v225, s[36:37]
	s_add_i32 s27, s22, 3
	s_min_i32 s27, s27, 0xff
	s_mul_i32 s27, s27, 0x60000
	v_add_u32_e32 v226, s27, v231
	global_load_dwordx4 v[170:173], v226, s[34:35]
	global_load_dwordx4 v[174:177], v226, s[36:37]
	s_add_i32 s27, s22, 4
	s_min_i32 s27, s27, 0xff
	s_mul_i32 s27, s27, 0x60000
	v_add_u32_e32 v227, s27, v231
	global_load_dwordx4 v[178:181], v227, s[34:35]
	global_load_dwordx4 v[182:185], v227, s[36:37]
	s_add_i32 s27, s22, 5
	s_min_i32 s27, s27, 0xff
	s_mul_i32 s27, s27, 0x60000
	v_add_u32_e32 v228, s27, v231
	global_load_dwordx4 v[186:189], v228, s[34:35]
	global_load_dwordx4 v[190:193], v228, s[36:37]
	global_load_dword v194, v247, s[38:39]
	global_load_dword v195, v248, s[38:39]
	s_waitcnt vmcnt(0)
.Lna_unit:
	s_lshr_b32 s54, s21, 6
	s_and_b32 s55, s21, 63
	s_lshr_b32 s56, s54, 4
	s_and_b32 s57, s54, 15
	s_lshl_b32 s58, s55, 2
	s_add_i32 s59, s58, -4
	s_max_i32 s59, s59, 0
	s_min_i32 s59, s59, 0xf8
	s_lshl_b32 s25, s30, 1
	s_add_i32 s25, s25, s58
	s_add_i32 s23, s25, -4
	s_max_i32 s23, s23, 0
	s_min_i32 s23, s23, 0xf8
	s_sub_i32 s24, s23, s59
	s_lshl_b32 s60, s56, 25
	s_lshl_b32 s61, s57, 7
	s_add_i32 s60, s60, s61
	s_add_u32 s16, s94, 0x17800000
	s_addc_u32 s17, s95, 0
	s_add_u32 s16, s16, s60
	s_addc_u32 s17, s17, 0
	v_lshrrev_b32_e32 v206, 4, v196
	v_add_u32_e32 v206, s25, v206
	v_add_u32_e32 v207, -4, v206
	v_med3_i32 v207, v207, 0, s18
	v_lshl_add_u32 v208, v206, 6, v198
	v_mov_b32_e32 v209, 0xf149f2ca
	s_waitcnt vmcnt(8)
	v_mul_f32_e32 v194, s13, v194
	v_cmp_eq_u32_e32 vcc, 1, v249
	s_nop 1
	v_cndmask_b32_e32 v194, 0, v194, vcc
	v_cmp_eq_u32_e32 vcc, 2, v249
	s_nop 1
	v_cndmask_b32_e32 v194, v194, v229, vcc
	v_mul_f32_e32 v195, s13, v195
	v_cmp_eq_u32_e32 vcc, 1, v250
	s_nop 1
	v_cndmask_b32_e32 v195, 0, v195, vcc
	v_cmp_eq_u32_e32 vcc, 2, v250
	s_nop 1
	v_cndmask_b32_e32 v195, v195, v229, vcc
	s_barrier
	ds_write_b128 v202, v[146:149]
	ds_write_b128 v202, v[150:153] offset:9216
	ds_write_b128 v202, v[154:157] offset:18432
	ds_write_b128 v202, v[158:161] offset:27648
	ds_write_b128 v202, v[162:165] offset:36864
	ds_write_b128 v202, v[166:169] offset:46080
	ds_write_b128 v203, v[170:173]
	ds_write_b128 v203, v[174:177] offset:9216
	ds_write_b128 v203, v[178:181] offset:18432
	ds_write_b128 v203, v[182:185] offset:27648
	ds_write_b128 v203, v[186:189] offset:36864
	ds_write_b128 v203, v[190:193] offset:46080
	ds_write_b32 v245, v194
	ds_write_b32 v246, v195
	s_waitcnt lgkmcnt(0)
	s_barrier
	s_waitcnt vmcnt(4)
	s_add_i32 s27, s22, 6
	s_min_i32 s27, s27, 0xff
	s_mul_i32 s27, s27, 0x60000
	v_add_u32_e32 v223, s27, v231
	global_load_dwordx4 v[146:149], v223, s[34:35]
	global_load_dwordx4 v[150:153], v223, s[36:37]
	s_add_i32 s27, s22, 7
	s_min_i32 s27, s27, 0xff
	s_mul_i32 s27, s27, 0x60000
	v_add_u32_e32 v224, s27, v231
	global_load_dwordx4 v[154:157], v224, s[34:35]
	global_load_dwordx4 v[158:161], v224, s[36:37]
	s_add_i32 s27, s22, 8
	s_min_i32 s27, s27, 0xff
	s_mul_i32 s27, s27, 0x60000
	v_add_u32_e32 v225, s27, v231
	global_load_dwordx4 v[162:165], v225, s[34:35]
	global_load_dwordx4 v[166:169], v225, s[36:37]
	s_add_i32 s27, s22, 9
	s_min_i32 s27, s27, 0xff
	s_mul_i32 s27, s27, 0x60000
	v_add_u32_e32 v226, s27, v231
	global_load_dwordx4 v[170:173], v226, s[34:35]
	global_load_dwordx4 v[174:177], v226, s[36:37]
	s_add_i32 s27, s22, 10
	s_min_i32 s27, s27, 0xff
	s_mul_i32 s27, s27, 0x60000
	v_add_u32_e32 v227, s27, v231
	global_load_dwordx4 v[178:181], v227, s[34:35]
	global_load_dwordx4 v[182:185], v227, s[36:37]
	s_cmp_lg_u32 s24, 0
	s_cbranch_scc1 .Lna_p1_d2
	s_nop 7
	s_nop 4
	ds_read_b128 v[114:117], v200
	ds_read_b128 v[118:121], v200 offset:32
	ds_read_b128 v[122:125], v200 offset:64
	ds_read_b128 v[126:129], v200 offset:96
	ds_read_b128 v[130:133], v200 offset:18432
	ds_read_b128 v[134:137], v200 offset:18464
	ds_read_b128 v[138:141], v200 offset:18496
	ds_read_b128 v[142:145], v200 offset:18528
	s_waitcnt lgkmcnt(7)
	v_mfma_f32_32x32x16_bf16 v[2:17], v[114:117], v[82:85], v[98:113]
	s_waitcnt lgkmcnt(6)
	v_mfma_f32_32x32x16_bf16 v[2:17], v[118:121], v[86:89], v[2:17]
	s_waitcnt lgkmcnt(5)
	v_mfma_f32_32x32x16_bf16 v[2:17], v[122:125], v[90:93], v[2:17]
	s_waitcnt lgkmcnt(4)
	v_mfma_f32_32x32x16_bf16 v[2:17], v[126:129], v[94:97], v[2:17]
	ds_read_b128 v[114:117], v200 offset:36864
	ds_read_b128 v[118:121], v200 offset:36896
	ds_read_b128 v[122:125], v200 offset:36928
	ds_read_b128 v[126:129], v200 offset:36960
	s_waitcnt lgkmcnt(7)
	v_mfma_f32_32x32x16_bf16 v[18:33], v[130:133], v[82:85], v[98:113]
	s_waitcnt lgkmcnt(6)
	v_mfma_f32_32x32x16_bf16 v[18:33], v[134:137], v[86:89], v[18:33]
	s_waitcnt lgkmcnt(5)
	v_mfma_f32_32x32x16_bf16 v[18:33], v[138:141], v[90:93], v[18:33]
	s_waitcnt lgkmcnt(4)
	v_mfma_f32_32x32x16_bf16 v[18:33], v[142:145], v[94:97], v[18:33]
	s_waitcnt lgkmcnt(3)
	v_mfma_f32_32x32x16_bf16 v[34:49], v[114:117], v[82:85], v[98:113]
	s_waitcnt lgkmcnt(2)
	v_mfma_f32_32x32x16_bf16 v[34:49], v[118:121], v[86:89], v[34:49]
	s_waitcnt lgkmcnt(1)
	v_mfma_f32_32x32x16_bf16 v[34:49], v[122:125], v[90:93], v[34:49]
	s_waitcnt lgkmcnt(0)
	v_mfma_f32_32x32x16_bf16 v[34:49], v[126:129], v[94:97], v[34:49]
	s_add_i32 s62, s23, 0
	s_add_i32 s64, s23, 1
	s_add_i32 s66, s23, 2
	s_add_i32 s63, s62, 7
	s_add_i32 s65, s64, 7
	s_add_i32 s67, s66, 7
	v_sub_u32_e32 v217, s63, v206
	v_sub_u32_e32 v219, s65, v206
	v_sub_u32_e32 v221, s67, v206
	v_sub_u32_e32 v218, s62, v207
	v_sub_u32_e32 v220, s64, v207
	v_sub_u32_e32 v222, s66, v207
	v_med3_i32 v217, v217, 0, 14
	v_med3_i32 v219, v219, 0, 14
	v_med3_i32 v221, v221, 0, 14
	v_cmp_gt_u32_e64 s[40:41], 8, v218
	v_cmp_gt_u32_e64 s[42:43], 8, v220
	v_cmp_gt_u32_e64 s[44:45], 8, v222
	v_mul_u32_u24_e32 v217, 31, v217
	v_mul_u32_u24_e32 v219, 31, v219
	v_mul_u32_u24_e32 v221, 31, v221
	v_add_u32_e32 v217, v217, v199
	v_add_u32_e32 v219, v219, v199
	v_add_u32_e32 v221, v221, v199
	v_lshlrev_b32_e32 v217, 2, v217
	v_lshlrev_b32_e32 v219, 2, v219
	v_lshlrev_b32_e32 v221, 2, v221
	v_add_u32_e32 v217, 110848, v217
	v_add_u32_e32 v219, 110848, v219
	v_add_u32_e32 v221, 110848, v221
	v_cndmask_b32_e64 v230, v244, v217, s[40:41]
	v_cndmask_b32_e64 v223, v244, v219, s[42:43]
	v_cndmask_b32_e64 v224, v244, v221, s[44:45]
	ds_read2_b32 v[114:115], v230 offset0:0 offset1:1
	ds_read2_b32 v[116:117], v230 offset0:2 offset1:3
	ds_read2_b32 v[118:119], v230 offset0:4 offset1:5
	ds_read2_b32 v[120:121], v230 offset0:6 offset1:7
	ds_read2_b32 v[122:123], v230 offset0:16 offset1:17
	ds_read2_b32 v[124:125], v230 offset0:18 offset1:19
	ds_read2_b32 v[126:127], v230 offset0:20 offset1:21
	ds_read2_b32 v[128:129], v230 offset0:22 offset1:23
	s_waitcnt lgkmcnt(7)
	v_fma_f32 v2, v2, s14, v114
	v_fma_f32 v3, v3, s14, v115
	s_waitcnt lgkmcnt(6)
	v_fma_f32 v4, v4, s14, v116
	v_fma_f32 v5, v5, s14, v117
	s_waitcnt lgkmcnt(5)
	v_fma_f32 v6, v6, s14, v118
	v_fma_f32 v7, v7, s14, v119
	s_waitcnt lgkmcnt(4)
	v_fma_f32 v8, v8, s14, v120
	v_fma_f32 v9, v9, s14, v121
	s_waitcnt lgkmcnt(3)
	v_fma_f32 v10, v10, s14, v122
	v_fma_f32 v11, v11, s14, v123
	s_waitcnt lgkmcnt(2)
	v_fma_f32 v12, v12, s14, v124
	v_fma_f32 v13, v13, s14, v125
	s_waitcnt lgkmcnt(1)
	v_fma_f32 v14, v14, s14, v126
	v_fma_f32 v15, v15, s14, v127
	s_waitcnt lgkmcnt(0)
	v_fma_f32 v16, v16, s14, v128
	v_fma_f32 v17, v17, s14, v129
	ds_read2_b32 v[130:131], v223 offset0:0 offset1:1
	ds_read2_b32 v[132:133], v223 offset0:2 offset1:3
	ds_read2_b32 v[134:135], v223 offset0:4 offset1:5
	ds_read2_b32 v[136:137], v223 offset0:6 offset1:7
	ds_read2_b32 v[138:139], v223 offset0:16 offset1:17
	ds_read2_b32 v[140:141], v223 offset0:18 offset1:19
	ds_read2_b32 v[142:143], v223 offset0:20 offset1:21
	ds_read2_b32 v[144:145], v223 offset0:22 offset1:23
	s_waitcnt lgkmcnt(7)
	v_fma_f32 v18, v18, s14, v130
	v_fma_f32 v19, v19, s14, v131
	s_waitcnt lgkmcnt(6)
	v_fma_f32 v20, v20, s14, v132
	v_fma_f32 v21, v21, s14, v133
	s_waitcnt lgkmcnt(5)
	v_fma_f32 v22, v22, s14, v134
	v_fma_f32 v23, v23, s14, v135
	s_waitcnt lgkmcnt(4)
	v_fma_f32 v24, v24, s14, v136
	v_fma_f32 v25, v25, s14, v137
	s_waitcnt lgkmcnt(3)
	v_fma_f32 v26, v26, s14, v138
	v_fma_f32 v27, v27, s14, v139
	s_waitcnt lgkmcnt(2)
	v_fma_f32 v28, v28, s14, v140
	v_fma_f32 v29, v29, s14, v141
	s_waitcnt lgkmcnt(1)
	v_fma_f32 v30, v30, s14, v142
	v_fma_f32 v31, v31, s14, v143
	s_waitcnt lgkmcnt(0)
	v_fma_f32 v32, v32, s14, v144
	v_fma_f32 v33, v33, s14, v145
	ds_read2_b32 v[114:115], v224 offset0:0 offset1:1
	ds_read2_b32 v[116:117], v224 offset0:2 offset1:3
	ds_read2_b32 v[118:119], v224 offset0:4 offset1:5
	ds_read2_b32 v[120:121], v224 offset0:6 offset1:7
	ds_read2_b32 v[122:123], v224 offset0:16 offset1:17
	ds_read2_b32 v[124:125], v224 offset0:18 offset1:19
	ds_read2_b32 v[126:127], v224 offset0:20 offset1:21
	ds_read2_b32 v[128:129], v224 offset0:22 offset1:23
	s_waitcnt lgkmcnt(7)
	v_fma_f32 v34, v34, s14, v114
	v_fma_f32 v35, v35, s14, v115
	s_waitcnt lgkmcnt(6)
	v_fma_f32 v36, v36, s14, v116
	v_fma_f32 v37, v37, s14, v117
	s_waitcnt lgkmcnt(5)
	v_fma_f32 v38, v38, s14, v118
	v_fma_f32 v39, v39, s14, v119
	s_waitcnt lgkmcnt(4)
	v_fma_f32 v40, v40, s14, v120
	v_fma_f32 v41, v41, s14, v121
	s_waitcnt lgkmcnt(3)
	v_fma_f32 v42, v42, s14, v122
	v_fma_f32 v43, v43, s14, v123
	s_waitcnt lgkmcnt(2)
	v_fma_f32 v44, v44, s14, v124
	v_fma_f32 v45, v45, s14, v125
	s_waitcnt lgkmcnt(1)
	v_fma_f32 v46, v46, s14, v126
	v_fma_f32 v47, v47, s14, v127
	s_waitcnt lgkmcnt(0)
	v_fma_f32 v48, v48, s14, v128
	v_fma_f32 v49, v49, s14, v129
	v_max3_f32 v210, v2, v3, v4
	v_max3_f32 v219, v5, v6, v7
	v_max3_f32 v220, v8, v9, v10
	v_max3_f32 v221, v11, v12, v13
	v_max3_f32 v210, v210, v14, v15
	v_max3_f32 v219, v219, v16, v17
	v_max3_f32 v220, v220, v18, v19
	v_max3_f32 v221, v221, v20, v21
	v_max3_f32 v210, v210, v22, v23
	v_max3_f32 v219, v219, v24, v25
	v_max3_f32 v220, v220, v26, v27
	v_max3_f32 v221, v221, v28, v29
	v_max3_f32 v210, v210, v30, v31
	v_max3_f32 v219, v219, v32, v33
	v_max3_f32 v220, v220, v34, v35
	v_max3_f32 v221, v221, v36, v37
	v_max3_f32 v210, v210, v38, v39
	v_max3_f32 v219, v219, v40, v41
	v_max3_f32 v220, v220, v42, v43
	v_max3_f32 v221, v221, v44, v45
	v_max3_f32 v210, v210, v46, v47
	v_max3_f32 v219, v219, v48, v49
	v_max_f32_e32 v210, v210, v219
	v_max_f32_e32 v220, v220, v221
	v_max_f32_e32 v210, v210, v220
	v_mov_b32_e32 v219, v210
	s_nop 1
	v_permlane32_swap_b32_e32 v210, v219
	v_max_f32_e32 v210, v210, v219
	v_max_f32_e32 v210, v210, v209
	v_mov_b32_e32 v209, v210
	v_mov_b32_e32 v213, 0
	v_mov_b32_e32 v214, 0
	v_mov_b32_e32 v215, 0
	v_mov_b32_e32 v216, 0
	v_sub_f32_e32 v2, v2, v209
	v_sub_f32_e32 v3, v3, v209
	v_sub_f32_e32 v4, v4, v209
	v_sub_f32_e32 v5, v5, v209
	v_sub_f32_e32 v6, v6, v209
	v_sub_f32_e32 v7, v7, v209
	v_sub_f32_e32 v8, v8, v209
	v_sub_f32_e32 v9, v9, v209
	v_exp_f32_e32 v2, v2
	v_exp_f32_e32 v3, v3
	v_exp_f32_e32 v4, v4
	v_exp_f32_e32 v5, v5
	v_exp_f32_e32 v6, v6
	v_exp_f32_e32 v7, v7
	v_exp_f32_e32 v8, v8
	v_exp_f32_e32 v9, v9
	v_add_f32_e32 v213, v213, v2
	v_add_f32_e32 v214, v214, v3
	v_add_f32_e32 v215, v215, v4
	v_add_f32_e32 v216, v216, v5
	v_add_f32_e32 v213, v213, v6
	v_add_f32_e32 v214, v214, v7
	v_add_f32_e32 v215, v215, v8
	v_add_f32_e32 v216, v216, v9
	v_cvt_pk_bf16_f32 v2, v2, v3
	v_cvt_pk_bf16_f32 v3, v4, v5
	v_cvt_pk_bf16_f32 v4, v6, v7
	v_cvt_pk_bf16_f32 v5, v8, v9
	v_sub_f32_e32 v10, v10, v209
	v_sub_f32_e32 v11, v11, v209
	v_sub_f32_e32 v12, v12, v209
	v_sub_f32_e32 v13, v13, v209
	v_sub_f32_e32 v14, v14, v209
	v_sub_f32_e32 v15, v15, v209
	v_sub_f32_e32 v16, v16, v209
	v_sub_f32_e32 v17, v17, v209
	v_exp_f32_e32 v10, v10
	v_exp_f32_e32 v11, v11
	v_exp_f32_e32 v12, v12
	v_exp_f32_e32 v13, v13
	v_exp_f32_e32 v14, v14
	v_exp_f32_e32 v15, v15
	v_exp_f32_e32 v16, v16
	v_exp_f32_e32 v17, v17
	v_add_f32_e32 v213, v213, v10
	v_add_f32_e32 v214, v214, v11
	v_add_f32_e32 v215, v215, v12
	v_add_f32_e32 v216, v216, v13
	v_add_f32_e32 v213, v213, v14
	v_add_f32_e32 v214, v214, v15
	v_add_f32_e32 v215, v215, v16
	v_add_f32_e32 v216, v216, v17
	v_cvt_pk_bf16_f32 v10, v10, v11
	v_cvt_pk_bf16_f32 v11, v12, v13
	v_cvt_pk_bf16_f32 v12, v14, v15
	v_cvt_pk_bf16_f32 v13, v16, v17
	v_sub_f32_e32 v18, v18, v209
	v_sub_f32_e32 v19, v19, v209
	v_sub_f32_e32 v20, v20, v209
	v_sub_f32_e32 v21, v21, v209
	v_sub_f32_e32 v22, v22, v209
	v_sub_f32_e32 v23, v23, v209
	v_sub_f32_e32 v24, v24, v209
	v_sub_f32_e32 v25, v25, v209
	v_exp_f32_e32 v18, v18
	v_exp_f32_e32 v19, v19
	v_exp_f32_e32 v20, v20
	v_exp_f32_e32 v21, v21
	v_exp_f32_e32 v22, v22
	v_exp_f32_e32 v23, v23
	v_exp_f32_e32 v24, v24
	v_exp_f32_e32 v25, v25
	v_add_f32_e32 v213, v213, v18
	v_add_f32_e32 v214, v214, v19
	v_add_f32_e32 v215, v215, v20
	v_add_f32_e32 v216, v216, v21
	v_add_f32_e32 v213, v213, v22
	v_add_f32_e32 v214, v214, v23
	v_add_f32_e32 v215, v215, v24
	v_add_f32_e32 v216, v216, v25
	v_cvt_pk_bf16_f32 v18, v18, v19
	v_cvt_pk_bf16_f32 v19, v20, v21
	v_cvt_pk_bf16_f32 v20, v22, v23
	v_cvt_pk_bf16_f32 v21, v24, v25
	v_sub_f32_e32 v26, v26, v209
	v_sub_f32_e32 v27, v27, v209
	v_sub_f32_e32 v28, v28, v209
	v_sub_f32_e32 v29, v29, v209
	v_sub_f32_e32 v30, v30, v209
	v_sub_f32_e32 v31, v31, v209
	v_sub_f32_e32 v32, v32, v209
	v_sub_f32_e32 v33, v33, v209
	v_exp_f32_e32 v26, v26
	v_exp_f32_e32 v27, v27
	v_exp_f32_e32 v28, v28
	v_exp_f32_e32 v29, v29
	v_exp_f32_e32 v30, v30
	v_exp_f32_e32 v31, v31
	v_exp_f32_e32 v32, v32
	v_exp_f32_e32 v33, v33
	v_add_f32_e32 v213, v213, v26
	v_add_f32_e32 v214, v214, v27
	v_add_f32_e32 v215, v215, v28
	v_add_f32_e32 v216, v216, v29
	v_add_f32_e32 v213, v213, v30
	v_add_f32_e32 v214, v214, v31
	v_add_f32_e32 v215, v215, v32
	v_add_f32_e32 v216, v216, v33
	v_cvt_pk_bf16_f32 v26, v26, v27
	v_cvt_pk_bf16_f32 v27, v28, v29
	v_cvt_pk_bf16_f32 v28, v30, v31
	v_cvt_pk_bf16_f32 v29, v32, v33
	v_sub_f32_e32 v34, v34, v209
	v_sub_f32_e32 v35, v35, v209
	v_sub_f32_e32 v36, v36, v209
	v_sub_f32_e32 v37, v37, v209
	v_sub_f32_e32 v38, v38, v209
	v_sub_f32_e32 v39, v39, v209
	v_sub_f32_e32 v40, v40, v209
	v_sub_f32_e32 v41, v41, v209
	v_exp_f32_e32 v34, v34
	v_exp_f32_e32 v35, v35
	v_exp_f32_e32 v36, v36
	v_exp_f32_e32 v37, v37
	v_exp_f32_e32 v38, v38
	v_exp_f32_e32 v39, v39
	v_exp_f32_e32 v40, v40
	v_exp_f32_e32 v41, v41
	v_add_f32_e32 v213, v213, v34
	v_add_f32_e32 v214, v214, v35
	v_add_f32_e32 v215, v215, v36
	v_add_f32_e32 v216, v216, v37
	v_add_f32_e32 v213, v213, v38
	v_add_f32_e32 v214, v214, v39
	v_add_f32_e32 v215, v215, v40
	v_add_f32_e32 v216, v216, v41
	v_cvt_pk_bf16_f32 v34, v34, v35
	v_cvt_pk_bf16_f32 v35, v36, v37
	v_cvt_pk_bf16_f32 v36, v38, v39
	v_cvt_pk_bf16_f32 v37, v40, v41
	v_sub_f32_e32 v42, v42, v209
	v_sub_f32_e32 v43, v43, v209
	v_sub_f32_e32 v44, v44, v209
	v_sub_f32_e32 v45, v45, v209
	v_sub_f32_e32 v46, v46, v209
	v_sub_f32_e32 v47, v47, v209
	v_sub_f32_e32 v48, v48, v209
	v_sub_f32_e32 v49, v49, v209
	v_exp_f32_e32 v42, v42
	v_exp_f32_e32 v43, v43
	v_exp_f32_e32 v44, v44
	v_exp_f32_e32 v45, v45
	v_exp_f32_e32 v46, v46
	v_exp_f32_e32 v47, v47
	v_exp_f32_e32 v48, v48
	v_exp_f32_e32 v49, v49
	v_add_f32_e32 v213, v213, v42
	v_add_f32_e32 v214, v214, v43
	v_add_f32_e32 v215, v215, v44
	v_add_f32_e32 v216, v216, v45
	v_add_f32_e32 v213, v213, v46
	v_add_f32_e32 v214, v214, v47
	v_add_f32_e32 v215, v215, v48
	v_add_f32_e32 v216, v216, v49
	v_cvt_pk_bf16_f32 v42, v42, v43
	v_cvt_pk_bf16_f32 v43, v44, v45
	v_cvt_pk_bf16_f32 v44, v46, v47
	v_cvt_pk_bf16_f32 v45, v48, v49
	v_add_f32_e32 v213, v213, v214
	v_add_f32_e32 v215, v215, v216
	v_add_f32_e32 v213, v213, v215
	v_mov_b32_e32 v212, v213
	ds_read_b64_tr_b16 v[114:115], v201 offset:9216
	ds_read_b64_tr_b16 v[116:117], v201 offset:9792
	ds_read_b64_tr_b16 v[118:119], v201 offset:9280
	ds_read_b64_tr_b16 v[120:121], v201 offset:9856
	ds_read_b64_tr_b16 v[122:123], v201 offset:11520
	ds_read_b64_tr_b16 v[124:125], v201 offset:12096
	ds_read_b64_tr_b16 v[126:127], v201 offset:11584
	ds_read_b64_tr_b16 v[128:129], v201 offset:12160
	ds_read_b64_tr_b16 v[130:131], v201 offset:27648
	ds_read_b64_tr_b16 v[132:133], v201 offset:28224
	ds_read_b64_tr_b16 v[134:135], v201 offset:27712
	ds_read_b64_tr_b16 v[136:137], v201 offset:28288
	s_waitcnt lgkmcnt(10)
	v_mfma_f32_32x32x16_bf16 v[50:65], v[114:117], v[2:5], 0
	s_waitcnt lgkmcnt(8)
	v_mfma_f32_32x32x16_bf16 v[66:81], v[118:121], v[2:5], 0
	ds_read_b64_tr_b16 v[138:139], v201 offset:29952
	ds_read_b64_tr_b16 v[140:141], v201 offset:30528
	ds_read_b64_tr_b16 v[142:143], v201 offset:30016
	ds_read_b64_tr_b16 v[144:145], v201 offset:30592
	s_waitcnt lgkmcnt(10)
	v_mfma_f32_32x32x16_bf16 v[50:65], v[122:125], v[10:13], v[50:65]
	s_waitcnt lgkmcnt(8)
	v_mfma_f32_32x32x16_bf16 v[66:81], v[126:129], v[10:13], v[66:81]
	ds_read_b64_tr_b16 v[114:115], v201 offset:46080
	ds_read_b64_tr_b16 v[116:117], v201 offset:46656
	ds_read_b64_tr_b16 v[118:119], v201 offset:46144
	ds_read_b64_tr_b16 v[120:121], v201 offset:46720
	s_waitcnt lgkmcnt(10)
	v_mfma_f32_32x32x16_bf16 v[50:65], v[130:133], v[18:21], v[50:65]
	s_waitcnt lgkmcnt(8)
	v_mfma_f32_32x32x16_bf16 v[66:81], v[134:137], v[18:21], v[66:81]
	ds_read_b64_tr_b16 v[122:123], v201 offset:48384
	ds_read_b64_tr_b16 v[124:125], v201 offset:48960
	ds_read_b64_tr_b16 v[126:127], v201 offset:48448
	ds_read_b64_tr_b16 v[128:129], v201 offset:49024
	s_waitcnt lgkmcnt(10)
	v_mfma_f32_32x32x16_bf16 v[50:65], v[138:141], v[26:29], v[50:65]
	s_waitcnt lgkmcnt(8)
	v_mfma_f32_32x32x16_bf16 v[66:81], v[142:145], v[26:29], v[66:81]
	s_waitcnt lgkmcnt(6)
	v_mfma_f32_32x32x16_bf16 v[50:65], v[114:117], v[34:37], v[50:65]
	s_waitcnt lgkmcnt(4)
	v_mfma_f32_32x32x16_bf16 v[66:81], v[118:121], v[34:37], v[66:81]
	s_waitcnt lgkmcnt(2)
	v_mfma_f32_32x32x16_bf16 v[50:65], v[122:125], v[42:45], v[50:65]
	s_waitcnt lgkmcnt(0)
	v_mfma_f32_32x32x16_bf16 v[66:81], v[126:129], v[42:45], v[66:81]
	s_nop 7
	s_nop 4
	ds_read_b128 v[114:117], v242
	ds_read_b128 v[118:121], v242 offset:32
	ds_read_b128 v[122:125], v242 offset:64
	ds_read_b128 v[126:129], v242 offset:96
	ds_read_b128 v[130:133], v242 offset:18432
	ds_read_b128 v[134:137], v242 offset:18464
	ds_read_b128 v[138:141], v242 offset:18496
	ds_read_b128 v[142:145], v242 offset:18528
	s_waitcnt lgkmcnt(7)
	v_mfma_f32_32x32x16_bf16 v[2:17], v[114:117], v[82:85], v[98:113]
	s_waitcnt lgkmcnt(6)
	v_mfma_f32_32x32x16_bf16 v[2:17], v[118:121], v[86:89], v[2:17]
	s_waitcnt lgkmcnt(5)
	v_mfma_f32_32x32x16_bf16 v[2:17], v[122:125], v[90:93], v[2:17]
	s_waitcnt lgkmcnt(4)
	v_mfma_f32_32x32x16_bf16 v[2:17], v[126:129], v[94:97], v[2:17]
	ds_read_b128 v[114:117], v242 offset:36864
	ds_read_b128 v[118:121], v242 offset:36896
	ds_read_b128 v[122:125], v242 offset:36928
	ds_read_b128 v[126:129], v242 offset:36960
	s_waitcnt lgkmcnt(7)
	v_mfma_f32_32x32x16_bf16 v[18:33], v[130:133], v[82:85], v[98:113]
	s_waitcnt lgkmcnt(6)
	v_mfma_f32_32x32x16_bf16 v[18:33], v[134:137], v[86:89], v[18:33]
	s_waitcnt lgkmcnt(5)
	v_mfma_f32_32x32x16_bf16 v[18:33], v[138:141], v[90:93], v[18:33]
	s_waitcnt lgkmcnt(4)
	v_mfma_f32_32x32x16_bf16 v[18:33], v[142:145], v[94:97], v[18:33]
	s_waitcnt lgkmcnt(3)
	v_mfma_f32_32x32x16_bf16 v[34:49], v[114:117], v[82:85], v[98:113]
	s_waitcnt lgkmcnt(2)
	v_mfma_f32_32x32x16_bf16 v[34:49], v[118:121], v[86:89], v[34:49]
	s_waitcnt lgkmcnt(1)
	v_mfma_f32_32x32x16_bf16 v[34:49], v[122:125], v[90:93], v[34:49]
	s_waitcnt lgkmcnt(0)
	v_mfma_f32_32x32x16_bf16 v[34:49], v[126:129], v[94:97], v[34:49]
	s_add_i32 s62, s23, 3
	s_add_i32 s64, s23, 4
	s_add_i32 s66, s23, 5
	s_add_i32 s63, s62, 7
	s_add_i32 s65, s64, 7
	s_add_i32 s67, s66, 7
	v_sub_u32_e32 v217, s63, v206
	v_sub_u32_e32 v219, s65, v206
	v_sub_u32_e32 v221, s67, v206
	v_sub_u32_e32 v218, s62, v207
	v_sub_u32_e32 v220, s64, v207
	v_sub_u32_e32 v222, s66, v207
	v_med3_i32 v217, v217, 0, 14
	v_med3_i32 v219, v219, 0, 14
	v_med3_i32 v221, v221, 0, 14
	v_cmp_gt_u32_e64 s[40:41], 8, v218
	v_cmp_gt_u32_e64 s[42:43], 8, v220
	v_cmp_gt_u32_e64 s[44:45], 8, v222
	v_mul_u32_u24_e32 v217, 31, v217
	v_mul_u32_u24_e32 v219, 31, v219
	v_mul_u32_u24_e32 v221, 31, v221
	v_add_u32_e32 v217, v217, v199
	v_add_u32_e32 v219, v219, v199
	v_add_u32_e32 v221, v221, v199
	v_lshlrev_b32_e32 v217, 2, v217
	v_lshlrev_b32_e32 v219, 2, v219
	v_lshlrev_b32_e32 v221, 2, v221
	v_add_u32_e32 v217, 110848, v217
	v_add_u32_e32 v219, 110848, v219
	v_add_u32_e32 v221, 110848, v221
	v_cndmask_b32_e64 v230, v244, v217, s[40:41]
	v_cndmask_b32_e64 v223, v244, v219, s[42:43]
	v_cndmask_b32_e64 v224, v244, v221, s[44:45]
	ds_read2_b32 v[114:115], v230 offset0:0 offset1:1
	ds_read2_b32 v[116:117], v230 offset0:2 offset1:3
	ds_read2_b32 v[118:119], v230 offset0:4 offset1:5
	ds_read2_b32 v[120:121], v230 offset0:6 offset1:7
	ds_read2_b32 v[122:123], v230 offset0:16 offset1:17
	ds_read2_b32 v[124:125], v230 offset0:18 offset1:19
	ds_read2_b32 v[126:127], v230 offset0:20 offset1:21
	ds_read2_b32 v[128:129], v230 offset0:22 offset1:23
	s_waitcnt lgkmcnt(7)
	v_fma_f32 v2, v2, s14, v114
	v_fma_f32 v3, v3, s14, v115
	s_waitcnt lgkmcnt(6)
	v_fma_f32 v4, v4, s14, v116
	v_fma_f32 v5, v5, s14, v117
	s_waitcnt lgkmcnt(5)
	v_fma_f32 v6, v6, s14, v118
	v_fma_f32 v7, v7, s14, v119
	s_waitcnt lgkmcnt(4)
	v_fma_f32 v8, v8, s14, v120
	v_fma_f32 v9, v9, s14, v121
	s_waitcnt lgkmcnt(3)
	v_fma_f32 v10, v10, s14, v122
	v_fma_f32 v11, v11, s14, v123
	s_waitcnt lgkmcnt(2)
	v_fma_f32 v12, v12, s14, v124
	v_fma_f32 v13, v13, s14, v125
	s_waitcnt lgkmcnt(1)
	v_fma_f32 v14, v14, s14, v126
	v_fma_f32 v15, v15, s14, v127
	s_waitcnt lgkmcnt(0)
	v_fma_f32 v16, v16, s14, v128
	v_fma_f32 v17, v17, s14, v129
	ds_read2_b32 v[130:131], v223 offset0:0 offset1:1
	ds_read2_b32 v[132:133], v223 offset0:2 offset1:3
	ds_read2_b32 v[134:135], v223 offset0:4 offset1:5
	ds_read2_b32 v[136:137], v223 offset0:6 offset1:7
	ds_read2_b32 v[138:139], v223 offset0:16 offset1:17
	ds_read2_b32 v[140:141], v223 offset0:18 offset1:19
	ds_read2_b32 v[142:143], v223 offset0:20 offset1:21
	ds_read2_b32 v[144:145], v223 offset0:22 offset1:23
	s_waitcnt lgkmcnt(7)
	v_fma_f32 v18, v18, s14, v130
	v_fma_f32 v19, v19, s14, v131
	s_waitcnt lgkmcnt(6)
	v_fma_f32 v20, v20, s14, v132
	v_fma_f32 v21, v21, s14, v133
	s_waitcnt lgkmcnt(5)
	v_fma_f32 v22, v22, s14, v134
	v_fma_f32 v23, v23, s14, v135
	s_waitcnt lgkmcnt(4)
	v_fma_f32 v24, v24, s14, v136
	v_fma_f32 v25, v25, s14, v137
	s_waitcnt lgkmcnt(3)
	v_fma_f32 v26, v26, s14, v138
	v_fma_f32 v27, v27, s14, v139
	s_waitcnt lgkmcnt(2)
	v_fma_f32 v28, v28, s14, v140
	v_fma_f32 v29, v29, s14, v141
	s_waitcnt lgkmcnt(1)
	v_fma_f32 v30, v30, s14, v142
	v_fma_f32 v31, v31, s14, v143
	s_waitcnt lgkmcnt(0)
	v_fma_f32 v32, v32, s14, v144
	v_fma_f32 v33, v33, s14, v145
	ds_read2_b32 v[114:115], v224 offset0:0 offset1:1
	ds_read2_b32 v[116:117], v224 offset0:2 offset1:3
	ds_read2_b32 v[118:119], v224 offset0:4 offset1:5
	ds_read2_b32 v[120:121], v224 offset0:6 offset1:7
	ds_read2_b32 v[122:123], v224 offset0:16 offset1:17
	ds_read2_b32 v[124:125], v224 offset0:18 offset1:19
	ds_read2_b32 v[126:127], v224 offset0:20 offset1:21
	ds_read2_b32 v[128:129], v224 offset0:22 offset1:23
	s_waitcnt lgkmcnt(7)
	v_fma_f32 v34, v34, s14, v114
	v_fma_f32 v35, v35, s14, v115
	s_waitcnt lgkmcnt(6)
	v_fma_f32 v36, v36, s14, v116
	v_fma_f32 v37, v37, s14, v117
	s_waitcnt lgkmcnt(5)
	v_fma_f32 v38, v38, s14, v118
	v_fma_f32 v39, v39, s14, v119
	s_waitcnt lgkmcnt(4)
	v_fma_f32 v40, v40, s14, v120
	v_fma_f32 v41, v41, s14, v121
	s_waitcnt lgkmcnt(3)
	v_fma_f32 v42, v42, s14, v122
	v_fma_f32 v43, v43, s14, v123
	s_waitcnt lgkmcnt(2)
	v_fma_f32 v44, v44, s14, v124
	v_fma_f32 v45, v45, s14, v125
	s_waitcnt lgkmcnt(1)
	v_fma_f32 v46, v46, s14, v126
	v_fma_f32 v47, v47, s14, v127
	s_waitcnt lgkmcnt(0)
	v_fma_f32 v48, v48, s14, v128
	v_fma_f32 v49, v49, s14, v129
	v_max3_f32 v210, v2, v3, v4
	v_max3_f32 v219, v5, v6, v7
	v_max3_f32 v220, v8, v9, v10
	v_max3_f32 v221, v11, v12, v13
	v_max3_f32 v210, v210, v14, v15
	v_max3_f32 v219, v219, v16, v17
	v_max3_f32 v220, v220, v18, v19
	v_max3_f32 v221, v221, v20, v21
	v_max3_f32 v210, v210, v22, v23
	v_max3_f32 v219, v219, v24, v25
	v_max3_f32 v220, v220, v26, v27
	v_max3_f32 v221, v221, v28, v29
	v_max3_f32 v210, v210, v30, v31
	v_max3_f32 v219, v219, v32, v33
	v_max3_f32 v220, v220, v34, v35
	v_max3_f32 v221, v221, v36, v37
	v_max3_f32 v210, v210, v38, v39
	v_max3_f32 v219, v219, v40, v41
	v_max3_f32 v220, v220, v42, v43
	v_max3_f32 v221, v221, v44, v45
	v_max3_f32 v210, v210, v46, v47
	v_max3_f32 v219, v219, v48, v49
	v_max_f32_e32 v210, v210, v219
	v_max_f32_e32 v220, v220, v221
	v_max_f32_e32 v210, v210, v220
	v_mov_b32_e32 v219, v210
	s_nop 1
	v_permlane32_swap_b32_e32 v210, v219
	v_max_f32_e32 v210, v210, v219
	v_max_f32_e32 v210, v210, v209
	v_sub_f32_e32 v211, v209, v210
	v_exp_f32_e32 v211, v211
	v_mov_b32_e32 v209, v210
	v_mul_f32_e32 v50, v50, v211
	v_mul_f32_e32 v51, v51, v211
	v_mul_f32_e32 v52, v52, v211
	v_mul_f32_e32 v53, v53, v211
	v_mul_f32_e32 v54, v54, v211
	v_mul_f32_e32 v55, v55, v211
	v_mul_f32_e32 v56, v56, v211
	v_mul_f32_e32 v57, v57, v211
	v_mul_f32_e32 v58, v58, v211
	v_mul_f32_e32 v59, v59, v211
	v_mul_f32_e32 v60, v60, v211
	v_mul_f32_e32 v61, v61, v211
	v_mul_f32_e32 v62, v62, v211
	v_mul_f32_e32 v63, v63, v211
	v_mul_f32_e32 v64, v64, v211
	v_mul_f32_e32 v65, v65, v211
	v_mul_f32_e32 v66, v66, v211
	v_mul_f32_e32 v67, v67, v211
	v_mul_f32_e32 v68, v68, v211
	v_mul_f32_e32 v69, v69, v211
	v_mul_f32_e32 v70, v70, v211
	v_mul_f32_e32 v71, v71, v211
	v_mul_f32_e32 v72, v72, v211
	v_mul_f32_e32 v73, v73, v211
	v_mul_f32_e32 v74, v74, v211
	v_mul_f32_e32 v75, v75, v211
	v_mul_f32_e32 v76, v76, v211
	v_mul_f32_e32 v77, v77, v211
	v_mul_f32_e32 v78, v78, v211
	v_mul_f32_e32 v79, v79, v211
	v_mul_f32_e32 v80, v80, v211
	v_mul_f32_e32 v81, v81, v211
	v_mul_f32_e32 v212, v212, v211
	v_mov_b32_e32 v213, 0
	v_mov_b32_e32 v214, 0
	v_mov_b32_e32 v215, 0
	v_mov_b32_e32 v216, 0
	v_sub_f32_e32 v2, v2, v209
	v_sub_f32_e32 v3, v3, v209
	v_sub_f32_e32 v4, v4, v209
	v_sub_f32_e32 v5, v5, v209
	v_sub_f32_e32 v6, v6, v209
	v_sub_f32_e32 v7, v7, v209
	v_sub_f32_e32 v8, v8, v209
	v_sub_f32_e32 v9, v9, v209
	v_exp_f32_e32 v2, v2
	v_exp_f32_e32 v3, v3
	v_exp_f32_e32 v4, v4
	v_exp_f32_e32 v5, v5
	v_exp_f32_e32 v6, v6
	v_exp_f32_e32 v7, v7
	v_exp_f32_e32 v8, v8
	v_exp_f32_e32 v9, v9
	v_add_f32_e32 v213, v213, v2
	v_add_f32_e32 v214, v214, v3
	v_add_f32_e32 v215, v215, v4
	v_add_f32_e32 v216, v216, v5
	v_add_f32_e32 v213, v213, v6
	v_add_f32_e32 v214, v214, v7
	v_add_f32_e32 v215, v215, v8
	v_add_f32_e32 v216, v216, v9
	v_cvt_pk_bf16_f32 v2, v2, v3
	v_cvt_pk_bf16_f32 v3, v4, v5
	v_cvt_pk_bf16_f32 v4, v6, v7
	v_cvt_pk_bf16_f32 v5, v8, v9
	v_sub_f32_e32 v10, v10, v209
	v_sub_f32_e32 v11, v11, v209
	v_sub_f32_e32 v12, v12, v209
	v_sub_f32_e32 v13, v13, v209
	v_sub_f32_e32 v14, v14, v209
	v_sub_f32_e32 v15, v15, v209
	v_sub_f32_e32 v16, v16, v209
	v_sub_f32_e32 v17, v17, v209
	v_exp_f32_e32 v10, v10
	v_exp_f32_e32 v11, v11
	v_exp_f32_e32 v12, v12
	v_exp_f32_e32 v13, v13
	v_exp_f32_e32 v14, v14
	v_exp_f32_e32 v15, v15
	v_exp_f32_e32 v16, v16
	v_exp_f32_e32 v17, v17
	v_add_f32_e32 v213, v213, v10
	v_add_f32_e32 v214, v214, v11
	v_add_f32_e32 v215, v215, v12
	v_add_f32_e32 v216, v216, v13
	v_add_f32_e32 v213, v213, v14
	v_add_f32_e32 v214, v214, v15
	v_add_f32_e32 v215, v215, v16
	v_add_f32_e32 v216, v216, v17
	v_cvt_pk_bf16_f32 v10, v10, v11
	v_cvt_pk_bf16_f32 v11, v12, v13
	v_cvt_pk_bf16_f32 v12, v14, v15
	v_cvt_pk_bf16_f32 v13, v16, v17
	v_sub_f32_e32 v18, v18, v209
	v_sub_f32_e32 v19, v19, v209
	v_sub_f32_e32 v20, v20, v209
	v_sub_f32_e32 v21, v21, v209
	v_sub_f32_e32 v22, v22, v209
	v_sub_f32_e32 v23, v23, v209
	v_sub_f32_e32 v24, v24, v209
	v_sub_f32_e32 v25, v25, v209
	v_exp_f32_e32 v18, v18
	v_exp_f32_e32 v19, v19
	v_exp_f32_e32 v20, v20
	v_exp_f32_e32 v21, v21
	v_exp_f32_e32 v22, v22
	v_exp_f32_e32 v23, v23
	v_exp_f32_e32 v24, v24
	v_exp_f32_e32 v25, v25
	v_add_f32_e32 v213, v213, v18
	v_add_f32_e32 v214, v214, v19
	v_add_f32_e32 v215, v215, v20
	v_add_f32_e32 v216, v216, v21
	v_add_f32_e32 v213, v213, v22
	v_add_f32_e32 v214, v214, v23
	v_add_f32_e32 v215, v215, v24
	v_add_f32_e32 v216, v216, v25
	v_cvt_pk_bf16_f32 v18, v18, v19
	v_cvt_pk_bf16_f32 v19, v20, v21
	v_cvt_pk_bf16_f32 v20, v22, v23
	v_cvt_pk_bf16_f32 v21, v24, v25
	v_sub_f32_e32 v26, v26, v209
	v_sub_f32_e32 v27, v27, v209
	v_sub_f32_e32 v28, v28, v209
	v_sub_f32_e32 v29, v29, v209
	v_sub_f32_e32 v30, v30, v209
	v_sub_f32_e32 v31, v31, v209
	v_sub_f32_e32 v32, v32, v209
	v_sub_f32_e32 v33, v33, v209
	v_exp_f32_e32 v26, v26
	v_exp_f32_e32 v27, v27
	v_exp_f32_e32 v28, v28
	v_exp_f32_e32 v29, v29
	v_exp_f32_e32 v30, v30
	v_exp_f32_e32 v31, v31
	v_exp_f32_e32 v32, v32
	v_exp_f32_e32 v33, v33
	v_add_f32_e32 v213, v213, v26
	v_add_f32_e32 v214, v214, v27
	v_add_f32_e32 v215, v215, v28
	v_add_f32_e32 v216, v216, v29
	v_add_f32_e32 v213, v213, v30
	v_add_f32_e32 v214, v214, v31
	v_add_f32_e32 v215, v215, v32
	v_add_f32_e32 v216, v216, v33
	v_cvt_pk_bf16_f32 v26, v26, v27
	v_cvt_pk_bf16_f32 v27, v28, v29
	v_cvt_pk_bf16_f32 v28, v30, v31
	v_cvt_pk_bf16_f32 v29, v32, v33
	v_sub_f32_e32 v34, v34, v209
	v_sub_f32_e32 v35, v35, v209
	v_sub_f32_e32 v36, v36, v209
	v_sub_f32_e32 v37, v37, v209
	v_sub_f32_e32 v38, v38, v209
	v_sub_f32_e32 v39, v39, v209
	v_sub_f32_e32 v40, v40, v209
	v_sub_f32_e32 v41, v41, v209
	v_exp_f32_e32 v34, v34
	v_exp_f32_e32 v35, v35
	v_exp_f32_e32 v36, v36
	v_exp_f32_e32 v37, v37
	v_exp_f32_e32 v38, v38
	v_exp_f32_e32 v39, v39
	v_exp_f32_e32 v40, v40
	v_exp_f32_e32 v41, v41
	v_add_f32_e32 v213, v213, v34
	v_add_f32_e32 v214, v214, v35
	v_add_f32_e32 v215, v215, v36
	v_add_f32_e32 v216, v216, v37
	v_add_f32_e32 v213, v213, v38
	v_add_f32_e32 v214, v214, v39
	v_add_f32_e32 v215, v215, v40
	v_add_f32_e32 v216, v216, v41
	v_cvt_pk_bf16_f32 v34, v34, v35
	v_cvt_pk_bf16_f32 v35, v36, v37
	v_cvt_pk_bf16_f32 v36, v38, v39
	v_cvt_pk_bf16_f32 v37, v40, v41
	v_sub_f32_e32 v42, v42, v209
	v_sub_f32_e32 v43, v43, v209
	v_sub_f32_e32 v44, v44, v209
	v_sub_f32_e32 v45, v45, v209
	v_sub_f32_e32 v46, v46, v209
	v_sub_f32_e32 v47, v47, v209
	v_sub_f32_e32 v48, v48, v209
	v_sub_f32_e32 v49, v49, v209
	v_exp_f32_e32 v42, v42
	v_exp_f32_e32 v43, v43
	v_exp_f32_e32 v44, v44
	v_exp_f32_e32 v45, v45
	v_exp_f32_e32 v46, v46
	v_exp_f32_e32 v47, v47
	v_exp_f32_e32 v48, v48
	v_exp_f32_e32 v49, v49
	v_add_f32_e32 v213, v213, v42
	v_add_f32_e32 v214, v214, v43
	v_add_f32_e32 v215, v215, v44
	v_add_f32_e32 v216, v216, v45
	v_add_f32_e32 v213, v213, v46
	v_add_f32_e32 v214, v214, v47
	v_add_f32_e32 v215, v215, v48
	v_add_f32_e32 v216, v216, v49
	v_cvt_pk_bf16_f32 v42, v42, v43
	v_cvt_pk_bf16_f32 v43, v44, v45
	v_cvt_pk_bf16_f32 v44, v46, v47
	v_cvt_pk_bf16_f32 v45, v48, v49
	v_add_f32_e32 v213, v213, v214
	v_add_f32_e32 v215, v215, v216
	v_add_f32_e32 v213, v213, v215
	v_add_f32_e32 v212, v212, v213
	ds_read_b64_tr_b16 v[114:115], v243 offset:9216
	ds_read_b64_tr_b16 v[116:117], v243 offset:9792
	ds_read_b64_tr_b16 v[118:119], v243 offset:9280
	ds_read_b64_tr_b16 v[120:121], v243 offset:9856
	ds_read_b64_tr_b16 v[122:123], v243 offset:11520
	ds_read_b64_tr_b16 v[124:125], v243 offset:12096
	ds_read_b64_tr_b16 v[126:127], v243 offset:11584
	ds_read_b64_tr_b16 v[128:129], v243 offset:12160
	ds_read_b64_tr_b16 v[130:131], v243 offset:27648
	ds_read_b64_tr_b16 v[132:133], v243 offset:28224
	ds_read_b64_tr_b16 v[134:135], v243 offset:27712
	ds_read_b64_tr_b16 v[136:137], v243 offset:28288
	s_waitcnt lgkmcnt(10)
	v_mfma_f32_32x32x16_bf16 v[50:65], v[114:117], v[2:5], v[50:65]
	s_waitcnt lgkmcnt(8)
	v_mfma_f32_32x32x16_bf16 v[66:81], v[118:121], v[2:5], v[66:81]
	ds_read_b64_tr_b16 v[138:139], v243 offset:29952
	ds_read_b64_tr_b16 v[140:141], v243 offset:30528
	ds_read_b64_tr_b16 v[142:143], v243 offset:30016
	ds_read_b64_tr_b16 v[144:145], v243 offset:30592
	s_waitcnt lgkmcnt(10)
	v_mfma_f32_32x32x16_bf16 v[50:65], v[122:125], v[10:13], v[50:65]
	s_waitcnt lgkmcnt(8)
	v_mfma_f32_32x32x16_bf16 v[66:81], v[126:129], v[10:13], v[66:81]
	ds_read_b64_tr_b16 v[114:115], v243 offset:46080
	ds_read_b64_tr_b16 v[116:117], v243 offset:46656
	ds_read_b64_tr_b16 v[118:119], v243 offset:46144
	ds_read_b64_tr_b16 v[120:121], v243 offset:46720
	s_waitcnt lgkmcnt(10)
	v_mfma_f32_32x32x16_bf16 v[50:65], v[130:133], v[18:21], v[50:65]
	s_waitcnt lgkmcnt(8)
	v_mfma_f32_32x32x16_bf16 v[66:81], v[134:137], v[18:21], v[66:81]
	ds_read_b64_tr_b16 v[122:123], v243 offset:48384
	ds_read_b64_tr_b16 v[124:125], v243 offset:48960
	ds_read_b64_tr_b16 v[126:127], v243 offset:48448
	ds_read_b64_tr_b16 v[128:129], v243 offset:49024
	s_waitcnt lgkmcnt(10)
	v_mfma_f32_32x32x16_bf16 v[50:65], v[138:141], v[26:29], v[50:65]
	s_waitcnt lgkmcnt(8)
	v_mfma_f32_32x32x16_bf16 v[66:81], v[142:145], v[26:29], v[66:81]
	s_waitcnt lgkmcnt(6)
	v_mfma_f32_32x32x16_bf16 v[50:65], v[114:117], v[34:37], v[50:65]
	s_waitcnt lgkmcnt(4)
	v_mfma_f32_32x32x16_bf16 v[66:81], v[118:121], v[34:37], v[66:81]
	s_waitcnt lgkmcnt(2)
	v_mfma_f32_32x32x16_bf16 v[50:65], v[122:125], v[42:45], v[50:65]
	s_waitcnt lgkmcnt(0)
	v_mfma_f32_32x32x16_bf16 v[66:81], v[126:129], v[42:45], v[66:81]
	s_branch .Lna_p1_end

.LBB0_1169:
	v_lshl_add_u32 v154, s28, 8, v1
	v_max_f32_e32 v122, 0, v122
	v_lshl_or_b32 v146, s60, 8, v149
	v_ashrrev_i32_e32 v155, 31, v154
	v_mul_f32_e32 v153, v122, v122
	v_max_f32_e32 v123, 0, v123
	v_max_f32_e32 v124, 0, v124
	v_ashrrev_i32_e32 v147, 31, v146
	v_lshlrev_b64 v[156:157], 13, v[154:155]
	v_max_f32_e32 v122, 0, v127
	v_mul_f32_e32 v127, v123, v123
	v_max_f32_e32 v123, v128, v128
	v_mul_f32_e32 v128, v124, v124
	v_lshl_add_u64 v[156:157], s[6:7], 0, v[156:157]
	v_lshlrev_b64 v[158:159], 1, v[146:147]
	v_max_f32_e32 v126, 0, v126
	v_mul_f32_e32 v122, v122, v122
	v_max_f32_e32 v123, 0, v123
	v_max_f32_e32 v124, 0, v129
	v_max_f32_e32 v125, 0, v125
	v_lshl_add_u64 v[146:147], v[156:157], 0, v[158:159]
	v_mul_f32_e32 v126, v126, v126
	v_mul_f32_e32 v123, v123, v123
	v_mul_f32_e32 v124, v124, v124
	v_mul_f32_e32 v125, v125, v125
	v_cvt_pk_bf16_f32 v122, v126, v122
	v_max_f32_e32 v114, 0, v114
	v_cvt_pk_bf16_f32 v123, v123, v124
	v_cvt_pk_bf16_f32 v124, v153, v127
	v_cvt_pk_bf16_f32 v125, v128, v125
	global_store_dwordx4 v[146:147], v[122:125], off
	v_max_f32_e32 v115, 0, v115
	v_max_f32_e32 v116, 0, v116
	v_mul_f32_e32 v122, v114, v114
	v_max_f32_e32 v114, 0, v119
	v_mul_f32_e32 v119, v115, v115
	v_max_f32_e32 v115, v120, v120
	v_mul_f32_e32 v120, v116, v116
	v_max_f32_e32 v118, 0, v118
	v_mul_f32_e32 v114, v114, v114
	v_max_f32_e32 v115, 0, v115
	v_max_f32_e32 v116, 0, v121
	v_max_f32_e32 v117, 0, v117
	v_mul_f32_e32 v118, v118, v118
	v_mul_f32_e32 v115, v115, v115
	v_mul_f32_e32 v116, v116, v116
	v_mul_f32_e32 v117, v117, v117
	v_cvt_pk_bf16_f32 v114, v118, v114
	v_cvt_pk_bf16_f32 v115, v115, v116
	v_cvt_pk_bf16_f32 v116, v122, v119
	v_cvt_pk_bf16_f32 v117, v120, v117
	global_store_dwordx4 v[146:147], v[114:117], off offset:256
	v_max_f32_e32 v106, 0, v106
	s_nop 0
	v_or_b32_e32 v114, 16, v154
	v_ashrrev_i32_e32 v115, 31, v114
	v_mul_f32_e32 v116, v106, v106
	v_max_f32_e32 v107, 0, v107
	v_max_f32_e32 v108, 0, v108
	v_lshlrev_b64 v[114:115], 13, v[114:115]
	v_max_f32_e32 v106, 0, v111
	v_mul_f32_e32 v111, v107, v107
	v_max_f32_e32 v107, v112, v112
	v_mul_f32_e32 v112, v108, v108
	v_lshl_add_u64 v[114:115], s[6:7], 0, v[114:115]
	v_max_f32_e32 v110, 0, v110
	v_mul_f32_e32 v106, v106, v106
	v_max_f32_e32 v107, 0, v107
	v_max_f32_e32 v108, 0, v113
	v_max_f32_e32 v109, 0, v109
	v_lshl_add_u64 v[114:115], v[114:115], 0, v[158:159]
	v_mul_f32_e32 v110, v110, v110
	v_mul_f32_e32 v107, v107, v107
	v_mul_f32_e32 v108, v108, v108
	v_mul_f32_e32 v109, v109, v109
	v_cvt_pk_bf16_f32 v106, v110, v106
	v_max_f32_e32 v98, 0, v98
	v_cvt_pk_bf16_f32 v107, v107, v108
	v_cvt_pk_bf16_f32 v108, v116, v111
	v_cvt_pk_bf16_f32 v109, v112, v109
	global_store_dwordx4 v[114:115], v[106:109], off
	v_max_f32_e32 v99, 0, v99
	v_max_f32_e32 v100, 0, v100
	v_mul_f32_e32 v106, v98, v98
	v_max_f32_e32 v98, 0, v103
	v_mul_f32_e32 v103, v99, v99
	v_max_f32_e32 v99, v104, v104
	v_mul_f32_e32 v104, v100, v100
	v_max_f32_e32 v102, 0, v102
	v_mul_f32_e32 v98, v98, v98
	v_max_f32_e32 v99, 0, v99
	v_max_f32_e32 v100, 0, v105
	v_max_f32_e32 v101, 0, v101
	v_mul_f32_e32 v102, v102, v102
	v_mul_f32_e32 v99, v99, v99
	v_mul_f32_e32 v100, v100, v100
	v_mul_f32_e32 v101, v101, v101
	v_cvt_pk_bf16_f32 v98, v102, v98
	v_cvt_pk_bf16_f32 v99, v99, v100
	v_cvt_pk_bf16_f32 v100, v106, v103
	v_cvt_pk_bf16_f32 v101, v104, v101
	global_store_dwordx4 v[114:115], v[98:101], off offset:256
	v_max_f32_e32 v90, 0, v90
	s_nop 0
	v_or_b32_e32 v98, 32, v154
	v_ashrrev_i32_e32 v99, 31, v98
	v_mul_f32_e32 v100, v90, v90
	v_max_f32_e32 v91, 0, v91
	v_max_f32_e32 v92, 0, v92
	v_lshlrev_b64 v[98:99], 13, v[98:99]
	v_max_f32_e32 v90, 0, v95
	v_mul_f32_e32 v95, v91, v91
	v_max_f32_e32 v91, v96, v96
	v_mul_f32_e32 v96, v92, v92
	v_lshl_add_u64 v[98:99], s[6:7], 0, v[98:99]
	v_max_f32_e32 v94, 0, v94
	v_mul_f32_e32 v90, v90, v90
	v_max_f32_e32 v91, 0, v91
	v_max_f32_e32 v92, 0, v97
	v_max_f32_e32 v93, 0, v93
	v_lshl_add_u64 v[98:99], v[98:99], 0, v[158:159]
	v_mul_f32_e32 v94, v94, v94
	v_mul_f32_e32 v91, v91, v91
	v_mul_f32_e32 v92, v92, v92
	v_mul_f32_e32 v93, v93, v93
	v_cvt_pk_bf16_f32 v90, v94, v90
	v_max_f32_e32 v82, 0, v82
	v_cvt_pk_bf16_f32 v91, v91, v92
	v_cvt_pk_bf16_f32 v92, v100, v95
	v_cvt_pk_bf16_f32 v93, v96, v93
	global_store_dwordx4 v[98:99], v[90:93], off
	v_max_f32_e32 v83, 0, v83
	v_max_f32_e32 v84, 0, v84
	v_mul_f32_e32 v90, v82, v82
	v_max_f32_e32 v82, 0, v87
	v_mul_f32_e32 v87, v83, v83
	v_max_f32_e32 v83, v88, v88
	v_mul_f32_e32 v88, v84, v84
	v_max_f32_e32 v86, 0, v86
	v_mul_f32_e32 v82, v82, v82
	v_max_f32_e32 v83, 0, v83
	v_max_f32_e32 v84, 0, v89
	v_max_f32_e32 v85, 0, v85
	v_mul_f32_e32 v86, v86, v86
	v_mul_f32_e32 v83, v83, v83
	v_mul_f32_e32 v84, v84, v84
	v_mul_f32_e32 v85, v85, v85
	v_cvt_pk_bf16_f32 v82, v86, v82
	v_cvt_pk_bf16_f32 v83, v83, v84
	v_cvt_pk_bf16_f32 v84, v90, v87
	v_cvt_pk_bf16_f32 v85, v88, v85
	global_store_dwordx4 v[98:99], v[82:85], off offset:256
	v_max_f32_e32 v74, 0, v74
	s_nop 0
	v_or_b32_e32 v82, 48, v154
	v_ashrrev_i32_e32 v83, 31, v82
	v_mul_f32_e32 v84, v74, v74
	v_max_f32_e32 v75, 0, v75
	v_max_f32_e32 v76, 0, v76
	v_lshlrev_b64 v[82:83], 13, v[82:83]
	v_max_f32_e32 v74, 0, v79
	v_mul_f32_e32 v79, v75, v75
	v_max_f32_e32 v75, v80, v80
	v_mul_f32_e32 v80, v76, v76
	v_lshl_add_u64 v[82:83], s[6:7], 0, v[82:83]
	v_max_f32_e32 v78, 0, v78
	v_mul_f32_e32 v74, v74, v74
	v_max_f32_e32 v75, 0, v75
	v_max_f32_e32 v76, 0, v81
	v_max_f32_e32 v77, 0, v77
	v_lshl_add_u64 v[82:83], v[82:83], 0, v[158:159]
	v_mul_f32_e32 v78, v78, v78
	v_mul_f32_e32 v75, v75, v75
	v_mul_f32_e32 v76, v76, v76
	v_mul_f32_e32 v77, v77, v77
	v_cvt_pk_bf16_f32 v74, v78, v74
	v_max_f32_e32 v66, 0, v66
	v_max_f32_e32 v67, 0, v67
	v_max_f32_e32 v68, 0, v68
	v_cvt_pk_bf16_f32 v75, v75, v76
	v_cvt_pk_bf16_f32 v76, v84, v79
	v_cvt_pk_bf16_f32 v77, v80, v77
	global_store_dwordx4 v[82:83], v[74:77], off
	s_nop 1
	v_mul_f32_e32 v74, v66, v66
	v_max_f32_e32 v66, v71, v71
	v_mul_f32_e32 v71, v67, v67
	v_max_f32_e32 v67, v72, v72
	v_mul_f32_e32 v72, v68, v68
	v_max_f32_e32 v66, 0, v66
	v_max_f32_e32 v67, 0, v67
	v_max_f32_e32 v68, 0, v73
	v_max_f32_e32 v70, 0, v70
	v_mul_f32_e32 v66, v66, v66
	v_mul_f32_e32 v67, v67, v67
	v_max_f32_e32 v69, 0, v69
	v_mul_f32_e32 v68, v68, v68
	v_mul_f32_e32 v70, v70, v70
	v_mul_f32_e32 v69, v69, v69
	v_cvt_pk_bf16_f32 v66, v70, v66
	v_cvt_pk_bf16_f32 v67, v67, v68
	v_cvt_pk_bf16_f32 v68, v74, v71
	v_max_f32_e32 v58, 0, v58
	v_cvt_pk_bf16_f32 v69, v72, v69
	global_store_dwordx4 v[82:83], v[66:69], off offset:256
	v_max_f32_e32 v59, 0, v59
	s_nop 0
	v_mul_f32_e32 v68, v58, v58
	v_max_f32_e32 v60, 0, v60
	v_max_f32_e32 v62, 0, v62
	v_max_f32_e32 v58, 0, v63
	v_mul_f32_e32 v63, v59, v59
	v_max_f32_e32 v59, v64, v64
	v_mul_f32_e32 v64, v60, v60
	v_mul_f32_e32 v62, v62, v62
	v_mul_f32_e32 v58, v58, v58
	v_max_f32_e32 v59, 0, v59
	v_max_f32_e32 v60, 0, v65
	v_mul_f32_e32 v59, v59, v59
	v_max_f32_e32 v61, 0, v61
	v_mul_f32_e32 v60, v60, v60
	v_cvt_pk_bf16_f32 v58, v62, v58
	v_add_co_u32_e32 v62, vcc, s56, v146
	v_mul_f32_e32 v61, v61, v61
	v_cvt_pk_bf16_f32 v59, v59, v60
	v_cvt_pk_bf16_f32 v60, v68, v63
	v_addc_co_u32_e32 v63, vcc, 0, v147, vcc
	v_max_f32_e32 v50, 0, v50
	v_max_f32_e32 v51, 0, v51
	v_max_f32_e32 v52, 0, v52
	v_cvt_pk_bf16_f32 v61, v64, v61
	global_store_dwordx4 v[62:63], v[58:61], off
	s_nop 1
	v_mul_f32_e32 v58, v50, v50
	v_max_f32_e32 v50, v55, v55
	v_mul_f32_e32 v55, v51, v51
	v_max_f32_e32 v51, v56, v56
	v_mul_f32_e32 v56, v52, v52
	v_max_f32_e32 v50, 0, v50
	v_max_f32_e32 v51, 0, v51
	v_max_f32_e32 v52, 0, v57
	v_max_f32_e32 v54, 0, v54
	v_mul_f32_e32 v50, v50, v50
	v_mul_f32_e32 v51, v51, v51
	v_max_f32_e32 v53, 0, v53
	v_mul_f32_e32 v52, v52, v52
	v_lshl_add_u64 v[66:67], v[146:147], 0, s[12:13]
	v_mul_f32_e32 v54, v54, v54
	v_mul_f32_e32 v53, v53, v53
	v_cvt_pk_bf16_f32 v50, v54, v50
	v_cvt_pk_bf16_f32 v51, v51, v52
	v_cvt_pk_bf16_f32 v52, v58, v55
	v_max_f32_e32 v42, 0, v42
	v_cvt_pk_bf16_f32 v53, v56, v53
	global_store_dwordx4 v[66:67], v[50:53], off offset:256
	v_max_f32_e32 v43, 0, v43
	s_nop 0
	v_mul_f32_e32 v52, v42, v42
	v_max_f32_e32 v44, 0, v44
	v_max_f32_e32 v46, 0, v46
	v_max_f32_e32 v42, 0, v47
	v_mul_f32_e32 v47, v43, v43
	v_max_f32_e32 v43, v48, v48
	v_mul_f32_e32 v48, v44, v44
	v_mul_f32_e32 v46, v46, v46
	v_mul_f32_e32 v42, v42, v42
	v_max_f32_e32 v43, 0, v43
	v_max_f32_e32 v44, 0, v49
	v_mul_f32_e32 v43, v43, v43
	v_max_f32_e32 v45, 0, v45
	v_mul_f32_e32 v44, v44, v44
	v_cvt_pk_bf16_f32 v42, v46, v42
	v_add_co_u32_e32 v46, vcc, s57, v146
	v_mul_f32_e32 v45, v45, v45
	v_cvt_pk_bf16_f32 v43, v43, v44
	v_cvt_pk_bf16_f32 v44, v52, v47
	v_addc_co_u32_e32 v47, vcc, 0, v147, vcc
	v_max_f32_e32 v34, 0, v34
	v_max_f32_e32 v35, 0, v35
	v_max_f32_e32 v36, 0, v36
	v_cvt_pk_bf16_f32 v45, v48, v45
	global_store_dwordx4 v[46:47], v[42:45], off
	s_nop 1
	v_mul_f32_e32 v42, v34, v34
	v_max_f32_e32 v34, v39, v39
	v_mul_f32_e32 v39, v35, v35
	v_max_f32_e32 v35, v40, v40
	v_mul_f32_e32 v40, v36, v36
	v_max_f32_e32 v34, 0, v34
	v_max_f32_e32 v35, 0, v35
	v_max_f32_e32 v36, 0, v41
	v_max_f32_e32 v38, 0, v38
	v_mul_f32_e32 v34, v34, v34
	v_mul_f32_e32 v35, v35, v35
	v_max_f32_e32 v37, 0, v37
	v_mul_f32_e32 v36, v36, v36
	v_lshl_add_u64 v[50:51], v[146:147], 0, s[14:15]
	v_mul_f32_e32 v38, v38, v38
	v_mul_f32_e32 v37, v37, v37
	v_cvt_pk_bf16_f32 v34, v38, v34
	v_cvt_pk_bf16_f32 v35, v35, v36
	v_cvt_pk_bf16_f32 v36, v42, v39
	v_max_f32_e32 v26, 0, v26
	v_cvt_pk_bf16_f32 v37, v40, v37
	global_store_dwordx4 v[50:51], v[34:37], off offset:256
	v_max_f32_e32 v27, 0, v27
	s_nop 0
	v_mul_f32_e32 v36, v26, v26
	v_max_f32_e32 v28, 0, v28
	v_max_f32_e32 v30, 0, v30
	v_max_f32_e32 v26, 0, v31
	v_mul_f32_e32 v31, v27, v27
	v_max_f32_e32 v27, v32, v32
	v_mul_f32_e32 v32, v28, v28
	v_mul_f32_e32 v30, v30, v30
	v_mul_f32_e32 v26, v26, v26
	v_max_f32_e32 v27, 0, v27
	v_max_f32_e32 v28, 0, v33
	v_mul_f32_e32 v27, v27, v27
	v_max_f32_e32 v29, 0, v29
	v_mul_f32_e32 v28, v28, v28
	v_cvt_pk_bf16_f32 v26, v30, v26
	v_add_co_u32_e32 v30, vcc, s58, v146
	v_mul_f32_e32 v29, v29, v29
	v_cvt_pk_bf16_f32 v27, v27, v28
	v_cvt_pk_bf16_f32 v28, v36, v31
	v_addc_co_u32_e32 v31, vcc, 0, v147, vcc
	v_max_f32_e32 v18, 0, v18
	v_max_f32_e32 v19, 0, v19
	v_max_f32_e32 v20, 0, v20
	v_cvt_pk_bf16_f32 v29, v32, v29
	global_store_dwordx4 v[30:31], v[26:29], off
	s_nop 1
	v_mul_f32_e32 v26, v18, v18
	v_max_f32_e32 v18, v23, v23
	v_mul_f32_e32 v23, v19, v19
	v_max_f32_e32 v19, v24, v24
	v_mul_f32_e32 v24, v20, v20
	v_max_f32_e32 v18, 0, v18
	v_max_f32_e32 v19, 0, v19
	v_max_f32_e32 v20, 0, v25
	v_max_f32_e32 v22, 0, v22
	v_mul_f32_e32 v18, v18, v18
	v_mul_f32_e32 v19, v19, v19
	v_max_f32_e32 v21, 0, v21
	v_mul_f32_e32 v20, v20, v20
	v_lshl_add_u64 v[34:35], v[146:147], 0, s[16:17]
	v_mul_f32_e32 v22, v22, v22
	v_mul_f32_e32 v21, v21, v21
	v_cvt_pk_bf16_f32 v18, v22, v18
	v_cvt_pk_bf16_f32 v19, v19, v20
	v_cvt_pk_bf16_f32 v20, v26, v23
	v_max_f32_e32 v10, 0, v10
	v_cvt_pk_bf16_f32 v21, v24, v21
	global_store_dwordx4 v[34:35], v[18:21], off offset:256
	v_max_f32_e32 v11, 0, v11
	s_nop 0
	v_mul_f32_e32 v20, v10, v10
	v_max_f32_e32 v12, 0, v12
	v_max_f32_e32 v14, 0, v14
	v_max_f32_e32 v10, 0, v15
	v_mul_f32_e32 v15, v11, v11
	v_max_f32_e32 v11, v16, v16
	v_mul_f32_e32 v16, v12, v12
	v_mul_f32_e32 v14, v14, v14
	v_mul_f32_e32 v10, v10, v10
	v_max_f32_e32 v11, 0, v11
	v_max_f32_e32 v12, 0, v17
	v_mul_f32_e32 v11, v11, v11
	v_max_f32_e32 v13, 0, v13
	v_mul_f32_e32 v12, v12, v12
	v_cvt_pk_bf16_f32 v10, v14, v10
	v_add_co_u32_e32 v14, vcc, s59, v146
	v_mul_f32_e32 v13, v13, v13
	v_cvt_pk_bf16_f32 v11, v11, v12
	v_cvt_pk_bf16_f32 v12, v20, v15
	v_addc_co_u32_e32 v15, vcc, 0, v147, vcc
	v_max_f32_e32 v2, 0, v2
	v_max_f32_e32 v3, 0, v3
	v_max_f32_e32 v4, 0, v4
	v_cvt_pk_bf16_f32 v13, v16, v13
	global_store_dwordx4 v[14:15], v[10:13], off
	s_nop 1
	v_mul_f32_e32 v10, v2, v2
	v_max_f32_e32 v2, v7, v7
	v_mul_f32_e32 v7, v3, v3
	v_max_f32_e32 v3, v8, v8
	v_mul_f32_e32 v8, v4, v4
	v_max_f32_e32 v2, 0, v2
	v_max_f32_e32 v3, 0, v3
	v_max_f32_e32 v4, 0, v9
	v_max_f32_e32 v5, 0, v5
	v_lshl_add_u64 v[18:19], v[146:147], 0, s[18:19]
	v_max_f32_e32 v6, 0, v6
	v_mul_f32_e32 v2, v2, v2
	v_mul_f32_e32 v3, v3, v3
	v_mul_f32_e32 v4, v4, v4
	v_mul_f32_e32 v5, v5, v5
	s_andn2_b64 vcc, exec, s[0:1]
	s_mov_b64 s[0:1], -1
	v_mul_f32_e32 v6, v6, v6
	v_cvt_pk_bf16_f32 v2, v6, v2
	v_cvt_pk_bf16_f32 v3, v3, v4
	v_cvt_pk_bf16_f32 v4, v10, v7
	v_cvt_pk_bf16_f32 v5, v8, v5
	global_store_dwordx4 v[18:19], v[2:5], off offset:256
	s_cbranch_vccnz .LBB0_1158
	s_andn2_b64 vcc, exec, s[4:5]
	s_cbranch_vccnz .LBB0_1157
	s_barrier
	s_branch .LBB0_1157
